# v17: v16 + 24 provably redundant s_waitcnt lgkmcnt(0) (second of a pair around the phase barrier) removed from the GEMM K loops
# baseline (speedup 1.0000x reference)
.LBB0_193:
	ds_read_b128 v[130:133], v169
	ds_read_b128 v[134:137], v169 offset:1024
	ds_read_b128 v[138:141], v169 offset:2048
	ds_read_b128 v[142:145], v169 offset:3072
	ds_read_b128 v[170:173], v174
	ds_read_b128 v[180:183], v174 offset:1024
	ds_read_b128 v[184:187], v174 offset:2048
	ds_read_b128 v[188:191], v174 offset:3072
	s_add_u32 s30, s4, 0xfffc0080
	s_addc_u32 s31, s5, -1
	s_cmp_eq_u32 s54, 12
	s_cselect_b32 s35, s23, s31
	s_cselect_b32 s34, s38, s30
	s_cselect_b32 s31, s21, s53
	s_cselect_b32 s30, s39, s52
	v_lshl_add_u64 v[166:167], s[4:5], 0, v[158:159]
	s_add_i32 m0, s47, 0xc000
	ds_read_b128 v[192:195], v175
	ds_read_b128 v[196:199], v175 offset:1024
	ds_read_b128 v[200:203], v175 offset:2048
	ds_read_b128 v[204:207], v175 offset:3072
	ds_read_b128 v[208:211], v175 offset:4096
	ds_read_b128 v[212:215], v175 offset:5120
	ds_read_b128 v[216:219], v175 offset:6144
	ds_read_b128 v[220:223], v175 offset:7168
	global_load_lds_dwordx4 v[166:167], off
	v_lshl_add_u64 v[166:167], s[4:5], 0, v[160:161]
	s_add_i32 m0, s47, 0xe000
	s_nop 0
	global_load_lds_dwordx4 v[166:167], off
	s_waitcnt vmcnt(8)
	s_waitcnt lgkmcnt(0)
	s_barrier
	s_setprio 1
	v_mfma_f32_16x16x32_bf16 v[126:129], v[130:133], v[192:195], v[126:129]
	v_mfma_f32_16x16x32_bf16 v[122:125], v[138:141], v[192:195], v[122:125]
	v_mfma_f32_16x16x32_bf16 v[110:113], v[130:133], v[200:203], v[110:113]
	v_mfma_f32_16x16x32_bf16 v[106:109], v[138:141], v[200:203], v[106:109]
	v_mfma_f32_16x16x32_bf16 v[94:97], v[130:133], v[208:211], v[94:97]
	v_mfma_f32_16x16x32_bf16 v[90:93], v[138:141], v[208:211], v[90:93]
	v_mfma_f32_16x16x32_bf16 v[78:81], v[130:133], v[216:219], v[78:81]
	v_mfma_f32_16x16x32_bf16 v[74:77], v[138:141], v[216:219], v[74:77]
	v_mfma_f32_16x16x32_bf16 v[126:129], v[134:137], v[196:199], v[126:129]
	v_mfma_f32_16x16x32_bf16 v[122:125], v[142:145], v[196:199], v[122:125]
	v_mfma_f32_16x16x32_bf16 v[110:113], v[134:137], v[204:207], v[110:113]
	v_mfma_f32_16x16x32_bf16 v[106:109], v[142:145], v[204:207], v[106:109]
	v_mfma_f32_16x16x32_bf16 v[94:97], v[134:137], v[212:215], v[94:97]
	v_mfma_f32_16x16x32_bf16 v[90:93], v[142:145], v[212:215], v[90:93]
	v_mfma_f32_16x16x32_bf16 v[78:81], v[134:137], v[220:223], v[78:81]
	v_mfma_f32_16x16x32_bf16 v[74:77], v[142:145], v[220:223], v[74:77]
	s_setprio 0
	s_setprio 1
	v_mfma_f32_16x16x32_bf16 v[118:121], v[170:173], v[192:195], v[118:121]
	v_mfma_f32_16x16x32_bf16 v[114:117], v[184:187], v[192:195], v[114:117]
	v_mfma_f32_16x16x32_bf16 v[102:105], v[170:173], v[200:203], v[102:105]
	v_mfma_f32_16x16x32_bf16 v[98:101], v[184:187], v[200:203], v[98:101]
	v_mfma_f32_16x16x32_bf16 v[86:89], v[170:173], v[208:211], v[86:89]
	v_mfma_f32_16x16x32_bf16 v[82:85], v[184:187], v[208:211], v[82:85]
	v_mfma_f32_16x16x32_bf16 v[70:73], v[170:173], v[216:219], v[70:73]
	v_mfma_f32_16x16x32_bf16 v[66:69], v[184:187], v[216:219], v[66:69]
	v_mfma_f32_16x16x32_bf16 v[118:121], v[180:183], v[196:199], v[118:121]
	v_mfma_f32_16x16x32_bf16 v[114:117], v[188:191], v[196:199], v[114:117]
	v_mfma_f32_16x16x32_bf16 v[102:105], v[180:183], v[204:207], v[102:105]
	v_mfma_f32_16x16x32_bf16 v[98:101], v[188:191], v[204:207], v[98:101]
	v_mfma_f32_16x16x32_bf16 v[86:89], v[180:183], v[212:215], v[86:89]
	v_mfma_f32_16x16x32_bf16 v[82:85], v[188:191], v[212:215], v[82:85]
	v_mfma_f32_16x16x32_bf16 v[70:73], v[180:183], v[220:223], v[70:73]
	v_mfma_f32_16x16x32_bf16 v[66:69], v[188:191], v[220:223], v[66:69]
	s_setprio 0
	s_barrier
	s_add_i32 s55, s64, s44
	v_lshl_add_u64 v[166:167], s[30:31], 0, v[148:149]
	s_mov_b32 m0, s55
	ds_read_b128 v[192:195], v175 offset:16384
	ds_read_b128 v[196:199], v175 offset:17408
	ds_read_b128 v[200:203], v175 offset:18432
	ds_read_b128 v[204:207], v175 offset:19456
	ds_read_b128 v[208:211], v175 offset:20480
	ds_read_b128 v[212:215], v175 offset:21504
	ds_read_b128 v[216:219], v175 offset:22528
	ds_read_b128 v[220:223], v175 offset:23552
	global_load_lds_dwordx4 v[166:167], off
	s_add_i32 m0, s55, 0x2000
	s_add_u32 s76, s30, 0x40000
	v_lshl_add_u64 v[224:225], s[30:31], 0, v[146:147]
	s_addc_u32 s77, s31, 0
	s_add_i32 s55, s65, s44
	global_load_lds_dwordx4 v[224:225], off
	v_lshl_add_u64 v[226:227], s[76:77], 0, v[148:149]
	s_mov_b32 m0, s55
	v_lshl_add_u64 v[228:229], s[34:35], 0, v[146:147]
	global_load_lds_dwordx4 v[226:227], off
	v_lshl_add_u64 v[226:227], s[76:77], 0, v[146:147]
	s_add_i32 m0, s55, 0x2000
	s_nop 0
	global_load_lds_dwordx4 v[226:227], off
	v_lshl_add_u64 v[226:227], s[34:35], 0, v[148:149]
	s_mov_b32 m0, s47
	s_nop 0
	global_load_lds_dwordx4 v[226:227], off
	s_mov_b32 m0, s36
	s_nop 0
	global_load_lds_dwordx4 v[228:229], off
	s_waitcnt vmcnt(8)
	s_waitcnt lgkmcnt(0)
	s_barrier
	s_setprio 1
	v_mfma_f32_16x16x32_bf16 v[62:65], v[130:133], v[192:195], v[62:65]
	v_mfma_f32_16x16x32_bf16 v[58:61], v[138:141], v[192:195], v[58:61]
	v_mfma_f32_16x16x32_bf16 v[46:49], v[130:133], v[200:203], v[46:49]
	v_mfma_f32_16x16x32_bf16 v[42:45], v[138:141], v[200:203], v[42:45]
	v_mfma_f32_16x16x32_bf16 v[30:33], v[130:133], v[208:211], v[30:33]
	v_mfma_f32_16x16x32_bf16 v[26:29], v[138:141], v[208:211], v[26:29]
	v_mfma_f32_16x16x32_bf16 v[14:17], v[130:133], v[216:219], v[14:17]
	v_mfma_f32_16x16x32_bf16 v[10:13], v[138:141], v[216:219], v[10:13]
	v_mfma_f32_16x16x32_bf16 v[62:65], v[134:137], v[196:199], v[62:65]
	v_mfma_f32_16x16x32_bf16 v[58:61], v[142:145], v[196:199], v[58:61]
	v_mfma_f32_16x16x32_bf16 v[46:49], v[134:137], v[204:207], v[46:49]
	v_mfma_f32_16x16x32_bf16 v[42:45], v[142:145], v[204:207], v[42:45]
	v_mfma_f32_16x16x32_bf16 v[30:33], v[134:137], v[212:215], v[30:33]
	v_mfma_f32_16x16x32_bf16 v[26:29], v[142:145], v[212:215], v[26:29]
	v_mfma_f32_16x16x32_bf16 v[14:17], v[134:137], v[220:223], v[14:17]
	v_mfma_f32_16x16x32_bf16 v[10:13], v[142:145], v[220:223], v[10:13]
	s_setprio 0
	s_setprio 1
	v_mfma_f32_16x16x32_bf16 v[54:57], v[170:173], v[192:195], v[54:57]
	v_mfma_f32_16x16x32_bf16 v[50:53], v[184:187], v[192:195], v[50:53]
	v_mfma_f32_16x16x32_bf16 v[38:41], v[170:173], v[200:203], v[38:41]
	v_mfma_f32_16x16x32_bf16 v[34:37], v[184:187], v[200:203], v[34:37]
	v_mfma_f32_16x16x32_bf16 v[22:25], v[170:173], v[208:211], v[22:25]
	v_mfma_f32_16x16x32_bf16 v[18:21], v[184:187], v[208:211], v[18:21]
	v_mfma_f32_16x16x32_bf16 v[6:9], v[170:173], v[216:219], v[6:9]
	v_mfma_f32_16x16x32_bf16 v[2:5], v[184:187], v[216:219], v[2:5]
	v_mfma_f32_16x16x32_bf16 v[54:57], v[180:183], v[196:199], v[54:57]
	v_mfma_f32_16x16x32_bf16 v[50:53], v[188:191], v[196:199], v[50:53]
	v_mfma_f32_16x16x32_bf16 v[38:41], v[180:183], v[204:207], v[38:41]
	v_mfma_f32_16x16x32_bf16 v[34:37], v[188:191], v[204:207], v[34:37]
	v_mfma_f32_16x16x32_bf16 v[22:25], v[180:183], v[212:215], v[22:25]
	v_mfma_f32_16x16x32_bf16 v[18:21], v[188:191], v[212:215], v[18:21]
	v_mfma_f32_16x16x32_bf16 v[6:9], v[180:183], v[220:223], v[6:9]
	v_mfma_f32_16x16x32_bf16 v[2:5], v[188:191], v[220:223], v[2:5]
	s_setprio 0
	s_barrier
	s_add_i32 s55, 0, 0x18000
	s_add_i32 s76, 0, 0x1c000
	v_add_u32_e32 v142, s55, v153
	v_add_u32_e32 v150, s76, v153
	ds_read_b128 v[130:133], v142
	ds_read_b128 v[134:137], v142 offset:1024
	ds_read_b128 v[138:141], v142 offset:2048
	ds_read_b128 v[142:145], v142 offset:3072
	ds_read_b128 v[170:173], v150
	ds_read_b128 v[180:183], v150 offset:1024
	ds_read_b128 v[184:187], v150 offset:2048
	ds_read_b128 v[188:191], v150 offset:3072
	s_add_u32 s34, s34, 0x40000
	s_addc_u32 s35, s35, 0
	s_mov_b32 m0, s37
	v_lshl_add_u64 v[230:231], s[34:35], 0, v[148:149]
	ds_read_b128 v[192:195], v175 offset:32768
	ds_read_b128 v[196:199], v175 offset:33792
	ds_read_b128 v[200:203], v175 offset:34816
	ds_read_b128 v[204:207], v175 offset:35840
	ds_read_b128 v[208:211], v175 offset:36864
	ds_read_b128 v[212:215], v175 offset:37888
	ds_read_b128 v[216:219], v175 offset:38912
	ds_read_b128 v[220:223], v175 offset:39936
	global_load_lds_dwordx4 v[230:231], off
	v_lshl_add_u64 v[230:231], s[34:35], 0, v[146:147]
	s_mov_b32 m0, s42
	s_nop 0
	global_load_lds_dwordx4 v[230:231], off
	s_waitcnt vmcnt(8)
	s_waitcnt lgkmcnt(0)
	s_barrier
	s_setprio 1
	v_mfma_f32_16x16x32_bf16 v[126:129], v[130:133], v[192:195], v[126:129]
	v_mfma_f32_16x16x32_bf16 v[122:125], v[138:141], v[192:195], v[122:125]
	v_mfma_f32_16x16x32_bf16 v[110:113], v[130:133], v[200:203], v[110:113]
	v_mfma_f32_16x16x32_bf16 v[106:109], v[138:141], v[200:203], v[106:109]
	v_mfma_f32_16x16x32_bf16 v[94:97], v[130:133], v[208:211], v[94:97]
	v_mfma_f32_16x16x32_bf16 v[90:93], v[138:141], v[208:211], v[90:93]
	v_mfma_f32_16x16x32_bf16 v[78:81], v[130:133], v[216:219], v[78:81]
	v_mfma_f32_16x16x32_bf16 v[74:77], v[138:141], v[216:219], v[74:77]
	v_mfma_f32_16x16x32_bf16 v[126:129], v[134:137], v[196:199], v[126:129]
	v_mfma_f32_16x16x32_bf16 v[122:125], v[142:145], v[196:199], v[122:125]
	v_mfma_f32_16x16x32_bf16 v[110:113], v[134:137], v[204:207], v[110:113]
	v_mfma_f32_16x16x32_bf16 v[106:109], v[142:145], v[204:207], v[106:109]
	v_mfma_f32_16x16x32_bf16 v[94:97], v[134:137], v[212:215], v[94:97]
	v_mfma_f32_16x16x32_bf16 v[90:93], v[142:145], v[212:215], v[90:93]
	v_mfma_f32_16x16x32_bf16 v[78:81], v[134:137], v[220:223], v[78:81]
	v_mfma_f32_16x16x32_bf16 v[74:77], v[142:145], v[220:223], v[74:77]
	s_setprio 0
	s_setprio 1
	v_mfma_f32_16x16x32_bf16 v[118:121], v[170:173], v[192:195], v[118:121]
	v_mfma_f32_16x16x32_bf16 v[114:117], v[184:187], v[192:195], v[114:117]
	v_mfma_f32_16x16x32_bf16 v[102:105], v[170:173], v[200:203], v[102:105]
	v_mfma_f32_16x16x32_bf16 v[98:101], v[184:187], v[200:203], v[98:101]
	v_mfma_f32_16x16x32_bf16 v[86:89], v[170:173], v[208:211], v[86:89]
	v_mfma_f32_16x16x32_bf16 v[82:85], v[184:187], v[208:211], v[82:85]
	v_mfma_f32_16x16x32_bf16 v[70:73], v[170:173], v[216:219], v[70:73]
	v_mfma_f32_16x16x32_bf16 v[66:69], v[184:187], v[216:219], v[66:69]
	v_mfma_f32_16x16x32_bf16 v[118:121], v[180:183], v[196:199], v[118:121]
	v_mfma_f32_16x16x32_bf16 v[114:117], v[188:191], v[196:199], v[114:117]
	v_mfma_f32_16x16x32_bf16 v[102:105], v[180:183], v[204:207], v[102:105]
	v_mfma_f32_16x16x32_bf16 v[98:101], v[188:191], v[204:207], v[98:101]
	v_mfma_f32_16x16x32_bf16 v[86:89], v[180:183], v[212:215], v[86:89]
	v_mfma_f32_16x16x32_bf16 v[82:85], v[188:191], v[212:215], v[82:85]
	v_mfma_f32_16x16x32_bf16 v[70:73], v[180:183], v[220:223], v[70:73]
	v_mfma_f32_16x16x32_bf16 v[66:69], v[188:191], v[220:223], v[66:69]
	s_setprio 0
	s_barrier
	s_add_i32 s34, s55, s44
	v_lshl_add_u64 v[166:167], v[166:167], 0, s[14:15]
	s_mov_b32 m0, s34
	ds_read_b128 v[192:195], v175 offset:49152
	ds_read_b128 v[196:199], v175 offset:50176
	ds_read_b128 v[200:203], v175 offset:51200
	ds_read_b128 v[204:207], v175 offset:52224
	ds_read_b128 v[208:211], v175 offset:53248
	ds_read_b128 v[212:215], v175 offset:54272
	ds_read_b128 v[216:219], v175 offset:55296
	ds_read_b128 v[220:223], v175 offset:56320
	global_load_lds_dwordx4 v[166:167], off
	s_add_i32 m0, s34, 0x2000
	s_add_u32 s30, s30, 0x40080
	v_lshl_add_u64 v[166:167], v[224:225], 0, s[14:15]
	s_addc_u32 s31, s31, 0
	s_add_i32 s34, s76, s44
	global_load_lds_dwordx4 v[166:167], off
	v_lshl_add_u64 v[166:167], s[30:31], 0, v[148:149]
	s_mov_b32 m0, s34
	s_nop 0
	global_load_lds_dwordx4 v[166:167], off
	v_lshl_add_u64 v[166:167], s[30:31], 0, v[146:147]
	s_add_i32 m0, s34, 0x2000
	s_nop 0
	global_load_lds_dwordx4 v[166:167], off
	v_lshl_add_u64 v[166:167], v[226:227], 0, s[14:15]
	s_mov_b32 m0, s43
	s_nop 0
	global_load_lds_dwordx4 v[166:167], off
	v_lshl_add_u64 v[166:167], v[228:229], 0, s[14:15]
	s_mov_b32 m0, s78
	s_nop 0
	global_load_lds_dwordx4 v[166:167], off
	s_waitcnt vmcnt(8)
	s_waitcnt lgkmcnt(0)
	s_barrier
	s_add_i32 s54, s54, 2
	s_add_u32 s4, s4, 0x100
	s_addc_u32 s5, s5, 0
	s_add_u32 s52, s52, 0x100
	s_addc_u32 s53, s53, 0
	s_cmp_gt_u32 s54, 13
	s_setprio 1
	s_waitcnt lgkmcnt(0)
	v_mfma_f32_16x16x32_bf16 v[62:65], v[130:133], v[192:195], v[62:65]
	v_mfma_f32_16x16x32_bf16 v[58:61], v[138:141], v[192:195], v[58:61]
	v_mfma_f32_16x16x32_bf16 v[46:49], v[130:133], v[200:203], v[46:49]
	v_mfma_f32_16x16x32_bf16 v[42:45], v[138:141], v[200:203], v[42:45]
	v_mfma_f32_16x16x32_bf16 v[30:33], v[130:133], v[208:211], v[30:33]
	v_mfma_f32_16x16x32_bf16 v[26:29], v[138:141], v[208:211], v[26:29]
	v_mfma_f32_16x16x32_bf16 v[14:17], v[130:133], v[216:219], v[14:17]
	v_mfma_f32_16x16x32_bf16 v[10:13], v[138:141], v[216:219], v[10:13]
	v_mfma_f32_16x16x32_bf16 v[62:65], v[134:137], v[196:199], v[62:65]
	v_mfma_f32_16x16x32_bf16 v[58:61], v[142:145], v[196:199], v[58:61]
	v_mfma_f32_16x16x32_bf16 v[46:49], v[134:137], v[204:207], v[46:49]
	v_mfma_f32_16x16x32_bf16 v[42:45], v[142:145], v[204:207], v[42:45]
	v_mfma_f32_16x16x32_bf16 v[30:33], v[134:137], v[212:215], v[30:33]
	v_mfma_f32_16x16x32_bf16 v[26:29], v[142:145], v[212:215], v[26:29]
	v_mfma_f32_16x16x32_bf16 v[14:17], v[134:137], v[220:223], v[14:17]
	v_mfma_f32_16x16x32_bf16 v[10:13], v[142:145], v[220:223], v[10:13]
	s_setprio 0
	s_setprio 1
	v_mfma_f32_16x16x32_bf16 v[54:57], v[170:173], v[192:195], v[54:57]
	v_mfma_f32_16x16x32_bf16 v[50:53], v[184:187], v[192:195], v[50:53]
	v_mfma_f32_16x16x32_bf16 v[38:41], v[170:173], v[200:203], v[38:41]
	v_mfma_f32_16x16x32_bf16 v[34:37], v[184:187], v[200:203], v[34:37]
	v_mfma_f32_16x16x32_bf16 v[22:25], v[170:173], v[208:211], v[22:25]
	v_mfma_f32_16x16x32_bf16 v[18:21], v[184:187], v[208:211], v[18:21]
	v_mfma_f32_16x16x32_bf16 v[6:9], v[170:173], v[216:219], v[6:9]
	v_mfma_f32_16x16x32_bf16 v[2:5], v[184:187], v[216:219], v[2:5]
	v_mfma_f32_16x16x32_bf16 v[54:57], v[180:183], v[196:199], v[54:57]
	v_mfma_f32_16x16x32_bf16 v[50:53], v[188:191], v[196:199], v[50:53]
	v_mfma_f32_16x16x32_bf16 v[38:41], v[180:183], v[204:207], v[38:41]
	v_mfma_f32_16x16x32_bf16 v[34:37], v[188:191], v[204:207], v[34:37]
	v_mfma_f32_16x16x32_bf16 v[22:25], v[180:183], v[212:215], v[22:25]
	v_mfma_f32_16x16x32_bf16 v[18:21], v[188:191], v[212:215], v[18:21]
	v_mfma_f32_16x16x32_bf16 v[6:9], v[180:183], v[220:223], v[6:9]
	v_mfma_f32_16x16x32_bf16 v[2:5], v[188:191], v[220:223], v[2:5]
	s_setprio 0
	s_barrier
	s_cbranch_scc0 .LBB0_193
	s_and_b64 vcc, exec, s[16:17]
	s_cbranch_vccz .LBB0_196
	s_barrier

.LBB0_518:
	ds_read_b128 v[154:157], v150
	ds_read_b128 v[158:161], v150 offset:1024
	ds_read_b128 v[162:165], v150 offset:2048
	ds_read_b128 v[166:169], v150 offset:3072
	ds_read_b128 v[170:173], v151
	ds_read_b128 v[174:177], v151 offset:1024
	ds_read_b128 v[178:181], v151 offset:2048
	ds_read_b128 v[182:185], v151 offset:3072
	s_add_u32 s26, s24, 0xfffd0080
	s_addc_u32 s27, s25, -1
	s_cmp_eq_u32 s63, 8
	s_cselect_b32 s29, s5, s27
	s_cselect_b32 s28, s4, s26
	s_cselect_b32 s27, s23, s62
	s_cselect_b32 s26, s22, s61
	v_lshl_add_u64 v[146:147], s[24:25], 0, v[138:139]
	s_add_i32 m0, s36, 0xc000
	ds_read_b128 v[186:189], v152
	ds_read_b128 v[190:193], v152 offset:1024
	ds_read_b128 v[194:197], v152 offset:2048
	ds_read_b128 v[198:201], v152 offset:3072
	ds_read_b128 v[202:205], v152 offset:4096
	ds_read_b128 v[206:209], v152 offset:5120
	ds_read_b128 v[210:213], v152 offset:6144
	ds_read_b128 v[214:217], v152 offset:7168
	global_load_lds_dwordx4 v[146:147], off
	v_lshl_add_u64 v[146:147], s[24:25], 0, v[140:141]
	s_add_i32 m0, s36, 0xe000
	s_nop 0
	global_load_lds_dwordx4 v[146:147], off
	s_waitcnt vmcnt(8)
	s_waitcnt lgkmcnt(0)
	s_barrier
	s_setprio 1
	v_mfma_f32_16x16x32_bf16 v[126:129], v[154:157], v[186:189], v[126:129]
	v_mfma_f32_16x16x32_bf16 v[122:125], v[162:165], v[186:189], v[122:125]
	v_mfma_f32_16x16x32_bf16 v[118:121], v[154:157], v[194:197], v[118:121]
	v_mfma_f32_16x16x32_bf16 v[110:113], v[162:165], v[194:197], v[110:113]
	v_mfma_f32_16x16x32_bf16 v[102:105], v[154:157], v[202:205], v[102:105]
	v_mfma_f32_16x16x32_bf16 v[94:97], v[162:165], v[202:205], v[94:97]
	v_mfma_f32_16x16x32_bf16 v[86:89], v[154:157], v[210:213], v[86:89]
	v_mfma_f32_16x16x32_bf16 v[78:81], v[162:165], v[210:213], v[78:81]
	v_mfma_f32_16x16x32_bf16 v[126:129], v[158:161], v[190:193], v[126:129]
	v_mfma_f32_16x16x32_bf16 v[122:125], v[166:169], v[190:193], v[122:125]
	v_mfma_f32_16x16x32_bf16 v[118:121], v[158:161], v[198:201], v[118:121]
	v_mfma_f32_16x16x32_bf16 v[110:113], v[166:169], v[198:201], v[110:113]
	v_mfma_f32_16x16x32_bf16 v[102:105], v[158:161], v[206:209], v[102:105]
	v_mfma_f32_16x16x32_bf16 v[94:97], v[166:169], v[206:209], v[94:97]
	v_mfma_f32_16x16x32_bf16 v[86:89], v[158:161], v[214:217], v[86:89]
	v_mfma_f32_16x16x32_bf16 v[78:81], v[166:169], v[214:217], v[78:81]
	s_setprio 0
	s_setprio 1
	v_mfma_f32_16x16x32_bf16 v[114:117], v[170:173], v[186:189], v[114:117]
	v_mfma_f32_16x16x32_bf16 v[106:109], v[178:181], v[186:189], v[106:109]
	v_mfma_f32_16x16x32_bf16 v[98:101], v[170:173], v[194:197], v[98:101]
	v_mfma_f32_16x16x32_bf16 v[90:93], v[178:181], v[194:197], v[90:93]
	v_mfma_f32_16x16x32_bf16 v[82:85], v[170:173], v[202:205], v[82:85]
	v_mfma_f32_16x16x32_bf16 v[74:77], v[178:181], v[202:205], v[74:77]
	v_mfma_f32_16x16x32_bf16 v[70:73], v[170:173], v[210:213], v[70:73]
	v_mfma_f32_16x16x32_bf16 v[66:69], v[178:181], v[210:213], v[66:69]
	v_mfma_f32_16x16x32_bf16 v[114:117], v[174:177], v[190:193], v[114:117]
	v_mfma_f32_16x16x32_bf16 v[106:109], v[182:185], v[190:193], v[106:109]
	v_mfma_f32_16x16x32_bf16 v[98:101], v[174:177], v[198:201], v[98:101]
	v_mfma_f32_16x16x32_bf16 v[90:93], v[182:185], v[198:201], v[90:93]
	v_mfma_f32_16x16x32_bf16 v[82:85], v[174:177], v[206:209], v[82:85]
	v_mfma_f32_16x16x32_bf16 v[74:77], v[182:185], v[206:209], v[74:77]
	v_mfma_f32_16x16x32_bf16 v[70:73], v[174:177], v[214:217], v[70:73]
	v_mfma_f32_16x16x32_bf16 v[66:69], v[182:185], v[214:217], v[66:69]
	s_setprio 0
	s_barrier
	s_add_i32 s64, s47, s35
	v_lshl_add_u64 v[146:147], s[26:27], 0, v[132:133]
	s_mov_b32 m0, s64
	ds_read_b128 v[186:189], v152 offset:16384
	ds_read_b128 v[190:193], v152 offset:17408
	ds_read_b128 v[194:197], v152 offset:18432
	ds_read_b128 v[198:201], v152 offset:19456
	ds_read_b128 v[202:205], v152 offset:20480
	ds_read_b128 v[206:209], v152 offset:21504
	ds_read_b128 v[210:213], v152 offset:22528
	ds_read_b128 v[214:217], v152 offset:23552
	global_load_lds_dwordx4 v[146:147], off
	s_add_i32 m0, s64, 0x2000
	s_add_u32 s64, s26, 0x30000
	v_lshl_add_u64 v[218:219], s[26:27], 0, v[136:137]
	s_addc_u32 s65, s27, 0
	s_add_i32 s66, s52, s35
	global_load_lds_dwordx4 v[218:219], off
	v_lshl_add_u64 v[220:221], s[64:65], 0, v[132:133]
	s_mov_b32 m0, s66
	v_lshl_add_u64 v[222:223], s[28:29], 0, v[134:135]
	global_load_lds_dwordx4 v[220:221], off
	v_lshl_add_u64 v[220:221], s[64:65], 0, v[136:137]
	s_add_i32 m0, s66, 0x2000
	s_nop 0
	global_load_lds_dwordx4 v[220:221], off
	v_lshl_add_u64 v[220:221], s[28:29], 0, v[130:131]
	s_mov_b32 m0, s36
	s_nop 0
	global_load_lds_dwordx4 v[220:221], off
	s_mov_b32 m0, s37
	s_nop 0
	global_load_lds_dwordx4 v[222:223], off
	s_waitcnt vmcnt(8)
	s_waitcnt lgkmcnt(0)
	s_barrier
	s_setprio 1
	v_mfma_f32_16x16x32_bf16 v[62:65], v[154:157], v[186:189], v[62:65]
	v_mfma_f32_16x16x32_bf16 v[58:61], v[162:165], v[186:189], v[58:61]
	v_mfma_f32_16x16x32_bf16 v[54:57], v[154:157], v[194:197], v[54:57]
	v_mfma_f32_16x16x32_bf16 v[46:49], v[162:165], v[194:197], v[46:49]
	v_mfma_f32_16x16x32_bf16 v[38:41], v[154:157], v[202:205], v[38:41]
	v_mfma_f32_16x16x32_bf16 v[30:33], v[162:165], v[202:205], v[30:33]
	v_mfma_f32_16x16x32_bf16 v[22:25], v[154:157], v[210:213], v[22:25]
	v_mfma_f32_16x16x32_bf16 v[14:17], v[162:165], v[210:213], v[14:17]
	v_mfma_f32_16x16x32_bf16 v[62:65], v[158:161], v[190:193], v[62:65]
	v_mfma_f32_16x16x32_bf16 v[58:61], v[166:169], v[190:193], v[58:61]
	v_mfma_f32_16x16x32_bf16 v[54:57], v[158:161], v[198:201], v[54:57]
	v_mfma_f32_16x16x32_bf16 v[46:49], v[166:169], v[198:201], v[46:49]
	v_mfma_f32_16x16x32_bf16 v[38:41], v[158:161], v[206:209], v[38:41]
	v_mfma_f32_16x16x32_bf16 v[30:33], v[166:169], v[206:209], v[30:33]
	v_mfma_f32_16x16x32_bf16 v[22:25], v[158:161], v[214:217], v[22:25]
	v_mfma_f32_16x16x32_bf16 v[14:17], v[166:169], v[214:217], v[14:17]
	s_setprio 0
	s_setprio 1
	v_mfma_f32_16x16x32_bf16 v[50:53], v[170:173], v[186:189], v[50:53]
	v_mfma_f32_16x16x32_bf16 v[42:45], v[178:181], v[186:189], v[42:45]
	v_mfma_f32_16x16x32_bf16 v[34:37], v[170:173], v[194:197], v[34:37]
	v_mfma_f32_16x16x32_bf16 v[26:29], v[178:181], v[194:197], v[26:29]
	v_mfma_f32_16x16x32_bf16 v[18:21], v[170:173], v[202:205], v[18:21]
	v_mfma_f32_16x16x32_bf16 v[10:13], v[178:181], v[202:205], v[10:13]
	v_mfma_f32_16x16x32_bf16 v[6:9], v[170:173], v[210:213], v[6:9]
	v_mfma_f32_16x16x32_bf16 v[2:5], v[178:181], v[210:213], v[2:5]
	v_mfma_f32_16x16x32_bf16 v[50:53], v[174:177], v[190:193], v[50:53]
	v_mfma_f32_16x16x32_bf16 v[42:45], v[182:185], v[190:193], v[42:45]
	v_mfma_f32_16x16x32_bf16 v[34:37], v[174:177], v[198:201], v[34:37]
	v_mfma_f32_16x16x32_bf16 v[26:29], v[182:185], v[198:201], v[26:29]
	v_mfma_f32_16x16x32_bf16 v[18:21], v[174:177], v[206:209], v[18:21]
	v_mfma_f32_16x16x32_bf16 v[10:13], v[182:185], v[206:209], v[10:13]
	v_mfma_f32_16x16x32_bf16 v[6:9], v[174:177], v[214:217], v[6:9]
	v_mfma_f32_16x16x32_bf16 v[2:5], v[182:185], v[214:217], v[2:5]
	s_setprio 0
	s_barrier
	s_add_i32 s64, 0, 0x18000
	v_add_u32_e32 v153, s64, v148
	s_add_i32 s65, 0, 0x1c000
	ds_read_b128 v[154:157], v153
	ds_read_b128 v[158:161], v153 offset:1024
	ds_read_b128 v[162:165], v153 offset:2048
	ds_read_b128 v[166:169], v153 offset:3072
	v_add_u32_e32 v153, s65, v148
	ds_read_b128 v[170:173], v153
	ds_read_b128 v[174:177], v153 offset:1024
	ds_read_b128 v[178:181], v153 offset:2048
	ds_read_b128 v[182:185], v153 offset:3072
	s_add_u32 s28, s28, 0x30000
	s_addc_u32 s29, s29, 0
	s_mov_b32 m0, s38
	v_lshl_add_u64 v[224:225], s[28:29], 0, v[130:131]
	ds_read_b128 v[186:189], v152 offset:32768
	ds_read_b128 v[190:193], v152 offset:33792
	ds_read_b128 v[194:197], v152 offset:34816
	ds_read_b128 v[198:201], v152 offset:35840
	ds_read_b128 v[202:205], v152 offset:36864
	ds_read_b128 v[206:209], v152 offset:37888
	ds_read_b128 v[210:213], v152 offset:38912
	ds_read_b128 v[214:217], v152 offset:39936
	global_load_lds_dwordx4 v[224:225], off
	v_lshl_add_u64 v[224:225], s[28:29], 0, v[134:135]
	s_mov_b32 m0, s39
	s_nop 0
	global_load_lds_dwordx4 v[224:225], off
	s_waitcnt vmcnt(8)
	s_waitcnt lgkmcnt(0)
	s_barrier
	s_setprio 1
	v_mfma_f32_16x16x32_bf16 v[126:129], v[154:157], v[186:189], v[126:129]
	v_mfma_f32_16x16x32_bf16 v[122:125], v[162:165], v[186:189], v[122:125]
	v_mfma_f32_16x16x32_bf16 v[118:121], v[154:157], v[194:197], v[118:121]
	v_mfma_f32_16x16x32_bf16 v[110:113], v[162:165], v[194:197], v[110:113]
	v_mfma_f32_16x16x32_bf16 v[102:105], v[154:157], v[202:205], v[102:105]
	v_mfma_f32_16x16x32_bf16 v[94:97], v[162:165], v[202:205], v[94:97]
	v_mfma_f32_16x16x32_bf16 v[86:89], v[154:157], v[210:213], v[86:89]
	v_mfma_f32_16x16x32_bf16 v[78:81], v[162:165], v[210:213], v[78:81]
	v_mfma_f32_16x16x32_bf16 v[126:129], v[158:161], v[190:193], v[126:129]
	v_mfma_f32_16x16x32_bf16 v[122:125], v[166:169], v[190:193], v[122:125]
	v_mfma_f32_16x16x32_bf16 v[118:121], v[158:161], v[198:201], v[118:121]
	v_mfma_f32_16x16x32_bf16 v[110:113], v[166:169], v[198:201], v[110:113]
	v_mfma_f32_16x16x32_bf16 v[102:105], v[158:161], v[206:209], v[102:105]
	v_mfma_f32_16x16x32_bf16 v[94:97], v[166:169], v[206:209], v[94:97]
	v_mfma_f32_16x16x32_bf16 v[86:89], v[158:161], v[214:217], v[86:89]
	v_mfma_f32_16x16x32_bf16 v[78:81], v[166:169], v[214:217], v[78:81]
	s_setprio 0
	s_setprio 1
	v_mfma_f32_16x16x32_bf16 v[114:117], v[170:173], v[186:189], v[114:117]
	v_mfma_f32_16x16x32_bf16 v[106:109], v[178:181], v[186:189], v[106:109]
	v_mfma_f32_16x16x32_bf16 v[98:101], v[170:173], v[194:197], v[98:101]
	v_mfma_f32_16x16x32_bf16 v[90:93], v[178:181], v[194:197], v[90:93]
	v_mfma_f32_16x16x32_bf16 v[82:85], v[170:173], v[202:205], v[82:85]
	v_mfma_f32_16x16x32_bf16 v[74:77], v[178:181], v[202:205], v[74:77]
	v_mfma_f32_16x16x32_bf16 v[70:73], v[170:173], v[210:213], v[70:73]
	v_mfma_f32_16x16x32_bf16 v[66:69], v[178:181], v[210:213], v[66:69]
	v_mfma_f32_16x16x32_bf16 v[114:117], v[174:177], v[190:193], v[114:117]
	v_mfma_f32_16x16x32_bf16 v[106:109], v[182:185], v[190:193], v[106:109]
	v_mfma_f32_16x16x32_bf16 v[98:101], v[174:177], v[198:201], v[98:101]
	v_mfma_f32_16x16x32_bf16 v[90:93], v[182:185], v[198:201], v[90:93]
	v_mfma_f32_16x16x32_bf16 v[82:85], v[174:177], v[206:209], v[82:85]
	v_mfma_f32_16x16x32_bf16 v[74:77], v[182:185], v[206:209], v[74:77]
	v_mfma_f32_16x16x32_bf16 v[70:73], v[174:177], v[214:217], v[70:73]
	v_mfma_f32_16x16x32_bf16 v[66:69], v[182:185], v[214:217], v[66:69]
	s_setprio 0
	s_barrier
	s_add_i32 s28, s64, s35
	v_lshl_add_u64 v[146:147], v[146:147], 0, s[10:11]
	s_mov_b32 m0, s28
	ds_read_b128 v[186:189], v152 offset:49152
	ds_read_b128 v[190:193], v152 offset:50176
	ds_read_b128 v[194:197], v152 offset:51200
	ds_read_b128 v[198:201], v152 offset:52224
	ds_read_b128 v[202:205], v152 offset:53248
	ds_read_b128 v[206:209], v152 offset:54272
	ds_read_b128 v[210:213], v152 offset:55296
	ds_read_b128 v[214:217], v152 offset:56320
	global_load_lds_dwordx4 v[146:147], off
	s_add_i32 m0, s28, 0x2000
	s_add_u32 s26, s26, 0x30080
	v_lshl_add_u64 v[146:147], v[218:219], 0, s[10:11]
	s_addc_u32 s27, s27, 0
	s_add_i32 s28, s65, s35
	global_load_lds_dwordx4 v[146:147], off
	v_lshl_add_u64 v[146:147], s[26:27], 0, v[132:133]
	s_mov_b32 m0, s28
	s_nop 0
	global_load_lds_dwordx4 v[146:147], off
	v_lshl_add_u64 v[146:147], s[26:27], 0, v[136:137]
	s_add_i32 m0, s28, 0x2000
	s_nop 0
	global_load_lds_dwordx4 v[146:147], off
	v_lshl_add_u64 v[146:147], v[220:221], 0, s[10:11]
	s_mov_b32 m0, s41
	s_nop 0
	global_load_lds_dwordx4 v[146:147], off
	v_lshl_add_u64 v[146:147], v[222:223], 0, s[10:11]
	s_mov_b32 m0, s44
	s_nop 0
	global_load_lds_dwordx4 v[146:147], off
	s_waitcnt vmcnt(8)
	s_waitcnt lgkmcnt(0)
	s_barrier
	s_add_i32 s63, s63, 2
	s_add_u32 s24, s24, 0x100
	s_addc_u32 s25, s25, 0
	s_add_u32 s61, s61, 0x100
	s_addc_u32 s62, s62, 0
	s_cmp_gt_u32 s63, 9
	s_setprio 1
	s_waitcnt lgkmcnt(0)
	v_mfma_f32_16x16x32_bf16 v[62:65], v[154:157], v[186:189], v[62:65]
	v_mfma_f32_16x16x32_bf16 v[58:61], v[162:165], v[186:189], v[58:61]
	v_mfma_f32_16x16x32_bf16 v[54:57], v[154:157], v[194:197], v[54:57]
	v_mfma_f32_16x16x32_bf16 v[46:49], v[162:165], v[194:197], v[46:49]
	v_mfma_f32_16x16x32_bf16 v[38:41], v[154:157], v[202:205], v[38:41]
	v_mfma_f32_16x16x32_bf16 v[30:33], v[162:165], v[202:205], v[30:33]
	v_mfma_f32_16x16x32_bf16 v[22:25], v[154:157], v[210:213], v[22:25]
	v_mfma_f32_16x16x32_bf16 v[14:17], v[162:165], v[210:213], v[14:17]
	v_mfma_f32_16x16x32_bf16 v[62:65], v[158:161], v[190:193], v[62:65]
	v_mfma_f32_16x16x32_bf16 v[58:61], v[166:169], v[190:193], v[58:61]
	v_mfma_f32_16x16x32_bf16 v[54:57], v[158:161], v[198:201], v[54:57]
	v_mfma_f32_16x16x32_bf16 v[46:49], v[166:169], v[198:201], v[46:49]
	v_mfma_f32_16x16x32_bf16 v[38:41], v[158:161], v[206:209], v[38:41]
	v_mfma_f32_16x16x32_bf16 v[30:33], v[166:169], v[206:209], v[30:33]
	v_mfma_f32_16x16x32_bf16 v[22:25], v[158:161], v[214:217], v[22:25]
	v_mfma_f32_16x16x32_bf16 v[14:17], v[166:169], v[214:217], v[14:17]
	s_setprio 0
	s_setprio 1
	v_mfma_f32_16x16x32_bf16 v[50:53], v[170:173], v[186:189], v[50:53]
	v_mfma_f32_16x16x32_bf16 v[42:45], v[178:181], v[186:189], v[42:45]
	v_mfma_f32_16x16x32_bf16 v[34:37], v[170:173], v[194:197], v[34:37]
	v_mfma_f32_16x16x32_bf16 v[26:29], v[178:181], v[194:197], v[26:29]
	v_mfma_f32_16x16x32_bf16 v[18:21], v[170:173], v[202:205], v[18:21]
	v_mfma_f32_16x16x32_bf16 v[10:13], v[178:181], v[202:205], v[10:13]
	v_mfma_f32_16x16x32_bf16 v[6:9], v[170:173], v[210:213], v[6:9]
	v_mfma_f32_16x16x32_bf16 v[2:5], v[178:181], v[210:213], v[2:5]
	v_mfma_f32_16x16x32_bf16 v[50:53], v[174:177], v[190:193], v[50:53]
	v_mfma_f32_16x16x32_bf16 v[42:45], v[182:185], v[190:193], v[42:45]
	v_mfma_f32_16x16x32_bf16 v[34:37], v[174:177], v[198:201], v[34:37]
	v_mfma_f32_16x16x32_bf16 v[26:29], v[182:185], v[198:201], v[26:29]
	v_mfma_f32_16x16x32_bf16 v[18:21], v[174:177], v[206:209], v[18:21]
	v_mfma_f32_16x16x32_bf16 v[10:13], v[182:185], v[206:209], v[10:13]
	v_mfma_f32_16x16x32_bf16 v[6:9], v[174:177], v[214:217], v[6:9]
	v_mfma_f32_16x16x32_bf16 v[2:5], v[182:185], v[214:217], v[2:5]
	s_setprio 0
	s_barrier
	s_cbranch_scc0 .LBB0_518
	s_and_b64 vcc, exec, s[12:13]
	s_cbranch_vccz .LBB0_521
	s_barrier

.LBB0_653:
	ds_read_b128 v[154:157], v150
	ds_read_b128 v[158:161], v150 offset:1024
	ds_read_b128 v[162:165], v150 offset:2048
	ds_read_b128 v[166:169], v150 offset:3072
	ds_read_b128 v[170:173], v151
	ds_read_b128 v[174:177], v151 offset:1024
	ds_read_b128 v[178:181], v151 offset:2048
	ds_read_b128 v[182:185], v151 offset:3072
	s_add_u32 s34, s30, 0xfffc0080
	s_addc_u32 s35, s31, -1
	s_cmp_eq_u32 s67, 12
	s_cselect_b32 s37, s23, s35
	s_cselect_b32 s36, s63, s34
	s_cselect_b32 s35, s21, s66
	s_cselect_b32 s34, s64, s65
	v_lshl_add_u64 v[146:147], s[30:31], 0, v[138:139]
	s_add_i32 m0, s29, 0xc000
	ds_read_b128 v[186:189], v152
	ds_read_b128 v[190:193], v152 offset:1024
	ds_read_b128 v[194:197], v152 offset:2048
	ds_read_b128 v[198:201], v152 offset:3072
	ds_read_b128 v[202:205], v152 offset:4096
	ds_read_b128 v[206:209], v152 offset:5120
	ds_read_b128 v[210:213], v152 offset:6144
	ds_read_b128 v[214:217], v152 offset:7168
	global_load_lds_dwordx4 v[146:147], off
	v_lshl_add_u64 v[146:147], s[30:31], 0, v[140:141]
	s_add_i32 m0, s29, 0xe000
	s_nop 0
	global_load_lds_dwordx4 v[146:147], off
	s_waitcnt vmcnt(8)
	s_waitcnt lgkmcnt(0)
	s_barrier
	s_setprio 1
	v_mfma_f32_16x16x32_bf16 v[126:129], v[154:157], v[186:189], v[126:129]
	v_mfma_f32_16x16x32_bf16 v[122:125], v[162:165], v[186:189], v[122:125]
	v_mfma_f32_16x16x32_bf16 v[110:113], v[154:157], v[194:197], v[110:113]
	v_mfma_f32_16x16x32_bf16 v[106:109], v[162:165], v[194:197], v[106:109]
	v_mfma_f32_16x16x32_bf16 v[94:97], v[154:157], v[202:205], v[94:97]
	v_mfma_f32_16x16x32_bf16 v[90:93], v[162:165], v[202:205], v[90:93]
	v_mfma_f32_16x16x32_bf16 v[78:81], v[154:157], v[210:213], v[78:81]
	v_mfma_f32_16x16x32_bf16 v[74:77], v[162:165], v[210:213], v[74:77]
	v_mfma_f32_16x16x32_bf16 v[126:129], v[158:161], v[190:193], v[126:129]
	v_mfma_f32_16x16x32_bf16 v[122:125], v[166:169], v[190:193], v[122:125]
	v_mfma_f32_16x16x32_bf16 v[110:113], v[158:161], v[198:201], v[110:113]
	v_mfma_f32_16x16x32_bf16 v[106:109], v[166:169], v[198:201], v[106:109]
	v_mfma_f32_16x16x32_bf16 v[94:97], v[158:161], v[206:209], v[94:97]
	v_mfma_f32_16x16x32_bf16 v[90:93], v[166:169], v[206:209], v[90:93]
	v_mfma_f32_16x16x32_bf16 v[78:81], v[158:161], v[214:217], v[78:81]
	v_mfma_f32_16x16x32_bf16 v[74:77], v[166:169], v[214:217], v[74:77]
	s_setprio 0
	s_setprio 1
	v_mfma_f32_16x16x32_bf16 v[118:121], v[170:173], v[186:189], v[118:121]
	v_mfma_f32_16x16x32_bf16 v[114:117], v[178:181], v[186:189], v[114:117]
	v_mfma_f32_16x16x32_bf16 v[102:105], v[170:173], v[194:197], v[102:105]
	v_mfma_f32_16x16x32_bf16 v[98:101], v[178:181], v[194:197], v[98:101]
	v_mfma_f32_16x16x32_bf16 v[86:89], v[170:173], v[202:205], v[86:89]
	v_mfma_f32_16x16x32_bf16 v[82:85], v[178:181], v[202:205], v[82:85]
	v_mfma_f32_16x16x32_bf16 v[70:73], v[170:173], v[210:213], v[70:73]
	v_mfma_f32_16x16x32_bf16 v[66:69], v[178:181], v[210:213], v[66:69]
	v_mfma_f32_16x16x32_bf16 v[118:121], v[174:177], v[190:193], v[118:121]
	v_mfma_f32_16x16x32_bf16 v[114:117], v[182:185], v[190:193], v[114:117]
	v_mfma_f32_16x16x32_bf16 v[102:105], v[174:177], v[198:201], v[102:105]
	v_mfma_f32_16x16x32_bf16 v[98:101], v[182:185], v[198:201], v[98:101]
	v_mfma_f32_16x16x32_bf16 v[86:89], v[174:177], v[206:209], v[86:89]
	v_mfma_f32_16x16x32_bf16 v[82:85], v[182:185], v[206:209], v[82:85]
	v_mfma_f32_16x16x32_bf16 v[70:73], v[174:177], v[214:217], v[70:73]
	v_mfma_f32_16x16x32_bf16 v[66:69], v[182:185], v[214:217], v[66:69]
	s_setprio 0
	s_barrier
	s_add_i32 s68, s56, s41
	v_lshl_add_u64 v[146:147], s[34:35], 0, v[132:133]
	s_mov_b32 m0, s68
	ds_read_b128 v[186:189], v152 offset:16384
	ds_read_b128 v[190:193], v152 offset:17408
	ds_read_b128 v[194:197], v152 offset:18432
	ds_read_b128 v[198:201], v152 offset:19456
	ds_read_b128 v[202:205], v152 offset:20480
	ds_read_b128 v[206:209], v152 offset:21504
	ds_read_b128 v[210:213], v152 offset:22528
	ds_read_b128 v[214:217], v152 offset:23552
	global_load_lds_dwordx4 v[146:147], off
	s_add_i32 m0, s68, 0x2000
	s_add_u32 s68, s34, 0x40000
	v_lshl_add_u64 v[218:219], s[34:35], 0, v[136:137]
	s_addc_u32 s69, s35, 0
	s_add_i32 s70, s57, s41
	global_load_lds_dwordx4 v[218:219], off
	v_lshl_add_u64 v[220:221], s[68:69], 0, v[132:133]
	s_mov_b32 m0, s70
	v_lshl_add_u64 v[222:223], s[36:37], 0, v[134:135]
	global_load_lds_dwordx4 v[220:221], off
	v_lshl_add_u64 v[220:221], s[68:69], 0, v[136:137]
	s_add_i32 m0, s70, 0x2000
	s_nop 0
	global_load_lds_dwordx4 v[220:221], off
	v_lshl_add_u64 v[220:221], s[36:37], 0, v[130:131]
	s_mov_b32 m0, s29
	s_nop 0
	global_load_lds_dwordx4 v[220:221], off
	s_mov_b32 m0, s44
	s_nop 0
	global_load_lds_dwordx4 v[222:223], off
	s_waitcnt vmcnt(8)
	s_waitcnt lgkmcnt(0)
	s_barrier
	s_setprio 1
	v_mfma_f32_16x16x32_bf16 v[62:65], v[154:157], v[186:189], v[62:65]
	v_mfma_f32_16x16x32_bf16 v[58:61], v[162:165], v[186:189], v[58:61]
	v_mfma_f32_16x16x32_bf16 v[46:49], v[154:157], v[194:197], v[46:49]
	v_mfma_f32_16x16x32_bf16 v[42:45], v[162:165], v[194:197], v[42:45]
	v_mfma_f32_16x16x32_bf16 v[30:33], v[154:157], v[202:205], v[30:33]
	v_mfma_f32_16x16x32_bf16 v[26:29], v[162:165], v[202:205], v[26:29]
	v_mfma_f32_16x16x32_bf16 v[14:17], v[154:157], v[210:213], v[14:17]
	v_mfma_f32_16x16x32_bf16 v[10:13], v[162:165], v[210:213], v[10:13]
	v_mfma_f32_16x16x32_bf16 v[62:65], v[158:161], v[190:193], v[62:65]
	v_mfma_f32_16x16x32_bf16 v[58:61], v[166:169], v[190:193], v[58:61]
	v_mfma_f32_16x16x32_bf16 v[46:49], v[158:161], v[198:201], v[46:49]
	v_mfma_f32_16x16x32_bf16 v[42:45], v[166:169], v[198:201], v[42:45]
	v_mfma_f32_16x16x32_bf16 v[30:33], v[158:161], v[206:209], v[30:33]
	v_mfma_f32_16x16x32_bf16 v[26:29], v[166:169], v[206:209], v[26:29]
	v_mfma_f32_16x16x32_bf16 v[14:17], v[158:161], v[214:217], v[14:17]
	v_mfma_f32_16x16x32_bf16 v[10:13], v[166:169], v[214:217], v[10:13]
	s_setprio 0
	s_setprio 1
	v_mfma_f32_16x16x32_bf16 v[54:57], v[170:173], v[186:189], v[54:57]
	v_mfma_f32_16x16x32_bf16 v[50:53], v[178:181], v[186:189], v[50:53]
	v_mfma_f32_16x16x32_bf16 v[38:41], v[170:173], v[194:197], v[38:41]
	v_mfma_f32_16x16x32_bf16 v[34:37], v[178:181], v[194:197], v[34:37]
	v_mfma_f32_16x16x32_bf16 v[22:25], v[170:173], v[202:205], v[22:25]
	v_mfma_f32_16x16x32_bf16 v[18:21], v[178:181], v[202:205], v[18:21]
	v_mfma_f32_16x16x32_bf16 v[6:9], v[170:173], v[210:213], v[6:9]
	v_mfma_f32_16x16x32_bf16 v[2:5], v[178:181], v[210:213], v[2:5]
	v_mfma_f32_16x16x32_bf16 v[54:57], v[174:177], v[190:193], v[54:57]
	v_mfma_f32_16x16x32_bf16 v[50:53], v[182:185], v[190:193], v[50:53]
	v_mfma_f32_16x16x32_bf16 v[38:41], v[174:177], v[198:201], v[38:41]
	v_mfma_f32_16x16x32_bf16 v[34:37], v[182:185], v[198:201], v[34:37]
	v_mfma_f32_16x16x32_bf16 v[22:25], v[174:177], v[206:209], v[22:25]
	v_mfma_f32_16x16x32_bf16 v[18:21], v[182:185], v[206:209], v[18:21]
	v_mfma_f32_16x16x32_bf16 v[6:9], v[174:177], v[214:217], v[6:9]
	v_mfma_f32_16x16x32_bf16 v[2:5], v[182:185], v[214:217], v[2:5]
	s_setprio 0
	s_barrier
	s_add_i32 s68, 0, 0x18000
	v_add_u32_e32 v153, s68, v148
	s_add_i32 s69, 0, 0x1c000
	ds_read_b128 v[154:157], v153
	ds_read_b128 v[158:161], v153 offset:1024
	ds_read_b128 v[162:165], v153 offset:2048
	ds_read_b128 v[166:169], v153 offset:3072
	v_add_u32_e32 v153, s69, v148
	ds_read_b128 v[170:173], v153
	ds_read_b128 v[174:177], v153 offset:1024
	ds_read_b128 v[178:181], v153 offset:2048
	ds_read_b128 v[182:185], v153 offset:3072
	s_add_u32 s36, s36, 0x40000
	s_addc_u32 s37, s37, 0
	s_mov_b32 m0, s45
	v_lshl_add_u64 v[224:225], s[36:37], 0, v[130:131]
	ds_read_b128 v[186:189], v152 offset:32768
	ds_read_b128 v[190:193], v152 offset:33792
	ds_read_b128 v[194:197], v152 offset:34816
	ds_read_b128 v[198:201], v152 offset:35840
	ds_read_b128 v[202:205], v152 offset:36864
	ds_read_b128 v[206:209], v152 offset:37888
	ds_read_b128 v[210:213], v152 offset:38912
	ds_read_b128 v[214:217], v152 offset:39936
	global_load_lds_dwordx4 v[224:225], off
	v_lshl_add_u64 v[224:225], s[36:37], 0, v[134:135]
	s_mov_b32 m0, s46
	s_nop 0
	global_load_lds_dwordx4 v[224:225], off
	s_waitcnt vmcnt(8)
	s_waitcnt lgkmcnt(0)
	s_barrier
	s_setprio 1
	v_mfma_f32_16x16x32_bf16 v[126:129], v[154:157], v[186:189], v[126:129]
	v_mfma_f32_16x16x32_bf16 v[122:125], v[162:165], v[186:189], v[122:125]
	v_mfma_f32_16x16x32_bf16 v[110:113], v[154:157], v[194:197], v[110:113]
	v_mfma_f32_16x16x32_bf16 v[106:109], v[162:165], v[194:197], v[106:109]
	v_mfma_f32_16x16x32_bf16 v[94:97], v[154:157], v[202:205], v[94:97]
	v_mfma_f32_16x16x32_bf16 v[90:93], v[162:165], v[202:205], v[90:93]
	v_mfma_f32_16x16x32_bf16 v[78:81], v[154:157], v[210:213], v[78:81]
	v_mfma_f32_16x16x32_bf16 v[74:77], v[162:165], v[210:213], v[74:77]
	v_mfma_f32_16x16x32_bf16 v[126:129], v[158:161], v[190:193], v[126:129]
	v_mfma_f32_16x16x32_bf16 v[122:125], v[166:169], v[190:193], v[122:125]
	v_mfma_f32_16x16x32_bf16 v[110:113], v[158:161], v[198:201], v[110:113]
	v_mfma_f32_16x16x32_bf16 v[106:109], v[166:169], v[198:201], v[106:109]
	v_mfma_f32_16x16x32_bf16 v[94:97], v[158:161], v[206:209], v[94:97]
	v_mfma_f32_16x16x32_bf16 v[90:93], v[166:169], v[206:209], v[90:93]
	v_mfma_f32_16x16x32_bf16 v[78:81], v[158:161], v[214:217], v[78:81]
	v_mfma_f32_16x16x32_bf16 v[74:77], v[166:169], v[214:217], v[74:77]
	s_setprio 0
	s_setprio 1
	v_mfma_f32_16x16x32_bf16 v[118:121], v[170:173], v[186:189], v[118:121]
	v_mfma_f32_16x16x32_bf16 v[114:117], v[178:181], v[186:189], v[114:117]
	v_mfma_f32_16x16x32_bf16 v[102:105], v[170:173], v[194:197], v[102:105]
	v_mfma_f32_16x16x32_bf16 v[98:101], v[178:181], v[194:197], v[98:101]
	v_mfma_f32_16x16x32_bf16 v[86:89], v[170:173], v[202:205], v[86:89]
	v_mfma_f32_16x16x32_bf16 v[82:85], v[178:181], v[202:205], v[82:85]
	v_mfma_f32_16x16x32_bf16 v[70:73], v[170:173], v[210:213], v[70:73]
	v_mfma_f32_16x16x32_bf16 v[66:69], v[178:181], v[210:213], v[66:69]
	v_mfma_f32_16x16x32_bf16 v[118:121], v[174:177], v[190:193], v[118:121]
	v_mfma_f32_16x16x32_bf16 v[114:117], v[182:185], v[190:193], v[114:117]
	v_mfma_f32_16x16x32_bf16 v[102:105], v[174:177], v[198:201], v[102:105]
	v_mfma_f32_16x16x32_bf16 v[98:101], v[182:185], v[198:201], v[98:101]
	v_mfma_f32_16x16x32_bf16 v[86:89], v[174:177], v[206:209], v[86:89]
	v_mfma_f32_16x16x32_bf16 v[82:85], v[182:185], v[206:209], v[82:85]
	v_mfma_f32_16x16x32_bf16 v[70:73], v[174:177], v[214:217], v[70:73]
	v_mfma_f32_16x16x32_bf16 v[66:69], v[182:185], v[214:217], v[66:69]
	s_setprio 0
	s_barrier
	s_add_i32 s36, s68, s41
	v_lshl_add_u64 v[146:147], v[146:147], 0, s[8:9]
	s_mov_b32 m0, s36
	ds_read_b128 v[186:189], v152 offset:49152
	ds_read_b128 v[190:193], v152 offset:50176
	ds_read_b128 v[194:197], v152 offset:51200
	ds_read_b128 v[198:201], v152 offset:52224
	ds_read_b128 v[202:205], v152 offset:53248
	ds_read_b128 v[206:209], v152 offset:54272
	ds_read_b128 v[210:213], v152 offset:55296
	ds_read_b128 v[214:217], v152 offset:56320
	global_load_lds_dwordx4 v[146:147], off
	s_add_i32 m0, s36, 0x2000
	s_add_u32 s34, s34, 0x40080
	v_lshl_add_u64 v[146:147], v[218:219], 0, s[8:9]
	s_addc_u32 s35, s35, 0
	s_add_i32 s36, s69, s41
	global_load_lds_dwordx4 v[146:147], off
	v_lshl_add_u64 v[146:147], s[34:35], 0, v[132:133]
	s_mov_b32 m0, s36
	s_nop 0
	global_load_lds_dwordx4 v[146:147], off
	v_lshl_add_u64 v[146:147], s[34:35], 0, v[136:137]
	s_add_i32 m0, s36, 0x2000
	s_nop 0
	global_load_lds_dwordx4 v[146:147], off
	v_lshl_add_u64 v[146:147], v[220:221], 0, s[8:9]
	s_mov_b32 m0, s52
	s_nop 0
	global_load_lds_dwordx4 v[146:147], off
	v_lshl_add_u64 v[146:147], v[222:223], 0, s[8:9]
	s_mov_b32 m0, s53
	s_nop 0
	global_load_lds_dwordx4 v[146:147], off
	s_waitcnt vmcnt(8)
	s_waitcnt lgkmcnt(0)
	s_barrier
	s_add_i32 s67, s67, 2
	s_add_u32 s30, s30, 0x100
	s_addc_u32 s31, s31, 0
	s_add_u32 s65, s65, 0x100
	s_addc_u32 s66, s66, 0
	s_cmp_gt_u32 s67, 13
	s_setprio 1
	s_waitcnt lgkmcnt(0)
	v_mfma_f32_16x16x32_bf16 v[62:65], v[154:157], v[186:189], v[62:65]
	v_mfma_f32_16x16x32_bf16 v[58:61], v[162:165], v[186:189], v[58:61]
	v_mfma_f32_16x16x32_bf16 v[46:49], v[154:157], v[194:197], v[46:49]
	v_mfma_f32_16x16x32_bf16 v[42:45], v[162:165], v[194:197], v[42:45]
	v_mfma_f32_16x16x32_bf16 v[30:33], v[154:157], v[202:205], v[30:33]
	v_mfma_f32_16x16x32_bf16 v[26:29], v[162:165], v[202:205], v[26:29]
	v_mfma_f32_16x16x32_bf16 v[14:17], v[154:157], v[210:213], v[14:17]
	v_mfma_f32_16x16x32_bf16 v[10:13], v[162:165], v[210:213], v[10:13]
	v_mfma_f32_16x16x32_bf16 v[62:65], v[158:161], v[190:193], v[62:65]
	v_mfma_f32_16x16x32_bf16 v[58:61], v[166:169], v[190:193], v[58:61]
	v_mfma_f32_16x16x32_bf16 v[46:49], v[158:161], v[198:201], v[46:49]
	v_mfma_f32_16x16x32_bf16 v[42:45], v[166:169], v[198:201], v[42:45]
	v_mfma_f32_16x16x32_bf16 v[30:33], v[158:161], v[206:209], v[30:33]
	v_mfma_f32_16x16x32_bf16 v[26:29], v[166:169], v[206:209], v[26:29]
	v_mfma_f32_16x16x32_bf16 v[14:17], v[158:161], v[214:217], v[14:17]
	v_mfma_f32_16x16x32_bf16 v[10:13], v[166:169], v[214:217], v[10:13]
	s_setprio 0
	s_setprio 1
	v_mfma_f32_16x16x32_bf16 v[54:57], v[170:173], v[186:189], v[54:57]
	v_mfma_f32_16x16x32_bf16 v[50:53], v[178:181], v[186:189], v[50:53]
	v_mfma_f32_16x16x32_bf16 v[38:41], v[170:173], v[194:197], v[38:41]
	v_mfma_f32_16x16x32_bf16 v[34:37], v[178:181], v[194:197], v[34:37]
	v_mfma_f32_16x16x32_bf16 v[22:25], v[170:173], v[202:205], v[22:25]
	v_mfma_f32_16x16x32_bf16 v[18:21], v[178:181], v[202:205], v[18:21]
	v_mfma_f32_16x16x32_bf16 v[6:9], v[170:173], v[210:213], v[6:9]
	v_mfma_f32_16x16x32_bf16 v[2:5], v[178:181], v[210:213], v[2:5]
	v_mfma_f32_16x16x32_bf16 v[54:57], v[174:177], v[190:193], v[54:57]
	v_mfma_f32_16x16x32_bf16 v[50:53], v[182:185], v[190:193], v[50:53]
	v_mfma_f32_16x16x32_bf16 v[38:41], v[174:177], v[198:201], v[38:41]
	v_mfma_f32_16x16x32_bf16 v[34:37], v[182:185], v[198:201], v[34:37]
	v_mfma_f32_16x16x32_bf16 v[22:25], v[174:177], v[206:209], v[22:25]
	v_mfma_f32_16x16x32_bf16 v[18:21], v[182:185], v[206:209], v[18:21]
	v_mfma_f32_16x16x32_bf16 v[6:9], v[174:177], v[214:217], v[6:9]
	v_mfma_f32_16x16x32_bf16 v[2:5], v[182:185], v[214:217], v[2:5]
	s_setprio 0
	s_barrier
	s_cbranch_scc0 .LBB0_653
	s_and_b64 vcc, exec, s[10:11]
	s_cbranch_vccz .LBB0_656
	s_barrier

.LBB0_728:
	ds_read_b128 v[154:157], v150
	ds_read_b128 v[158:161], v150 offset:1024
	ds_read_b128 v[162:165], v150 offset:2048
	ds_read_b128 v[166:169], v150 offset:3072
	ds_read_b128 v[170:173], v151
	ds_read_b128 v[174:177], v151 offset:1024
	ds_read_b128 v[178:181], v151 offset:2048
	ds_read_b128 v[182:185], v151 offset:3072
	s_add_u32 s34, s30, 0xfff00080
	s_addc_u32 s35, s31, -1
	s_cmp_eq_u32 s67, 60
	s_cselect_b32 s37, s23, s35
	s_cselect_b32 s36, s63, s34
	s_cselect_b32 s35, s21, s66
	s_cselect_b32 s34, s64, s65
	v_lshl_add_u64 v[146:147], s[30:31], 0, v[138:139]
	s_add_i32 m0, s29, 0xc000
	ds_read_b128 v[186:189], v152
	ds_read_b128 v[190:193], v152 offset:1024
	ds_read_b128 v[194:197], v152 offset:2048
	ds_read_b128 v[198:201], v152 offset:3072
	ds_read_b128 v[202:205], v152 offset:4096
	ds_read_b128 v[206:209], v152 offset:5120
	ds_read_b128 v[210:213], v152 offset:6144
	ds_read_b128 v[214:217], v152 offset:7168
	global_load_lds_dwordx4 v[146:147], off
	v_lshl_add_u64 v[146:147], s[30:31], 0, v[140:141]
	s_add_i32 m0, s29, 0xe000
	s_nop 0
	global_load_lds_dwordx4 v[146:147], off
	s_waitcnt vmcnt(8)
	s_waitcnt lgkmcnt(0)
	s_barrier
	s_setprio 1
	v_mfma_f32_16x16x32_bf16 v[126:129], v[154:157], v[186:189], v[126:129]
	v_mfma_f32_16x16x32_bf16 v[122:125], v[162:165], v[186:189], v[122:125]
	v_mfma_f32_16x16x32_bf16 v[118:121], v[154:157], v[194:197], v[118:121]
	v_mfma_f32_16x16x32_bf16 v[110:113], v[162:165], v[194:197], v[110:113]
	v_mfma_f32_16x16x32_bf16 v[102:105], v[154:157], v[202:205], v[102:105]
	v_mfma_f32_16x16x32_bf16 v[94:97], v[162:165], v[202:205], v[94:97]
	v_mfma_f32_16x16x32_bf16 v[86:89], v[154:157], v[210:213], v[86:89]
	v_mfma_f32_16x16x32_bf16 v[78:81], v[162:165], v[210:213], v[78:81]
	v_mfma_f32_16x16x32_bf16 v[126:129], v[158:161], v[190:193], v[126:129]
	v_mfma_f32_16x16x32_bf16 v[122:125], v[166:169], v[190:193], v[122:125]
	v_mfma_f32_16x16x32_bf16 v[118:121], v[158:161], v[198:201], v[118:121]
	v_mfma_f32_16x16x32_bf16 v[110:113], v[166:169], v[198:201], v[110:113]
	v_mfma_f32_16x16x32_bf16 v[102:105], v[158:161], v[206:209], v[102:105]
	v_mfma_f32_16x16x32_bf16 v[94:97], v[166:169], v[206:209], v[94:97]
	v_mfma_f32_16x16x32_bf16 v[86:89], v[158:161], v[214:217], v[86:89]
	v_mfma_f32_16x16x32_bf16 v[78:81], v[166:169], v[214:217], v[78:81]
	s_setprio 0
	s_setprio 1
	v_mfma_f32_16x16x32_bf16 v[114:117], v[170:173], v[186:189], v[114:117]
	v_mfma_f32_16x16x32_bf16 v[106:109], v[178:181], v[186:189], v[106:109]
	v_mfma_f32_16x16x32_bf16 v[98:101], v[170:173], v[194:197], v[98:101]
	v_mfma_f32_16x16x32_bf16 v[90:93], v[178:181], v[194:197], v[90:93]
	v_mfma_f32_16x16x32_bf16 v[82:85], v[170:173], v[202:205], v[82:85]
	v_mfma_f32_16x16x32_bf16 v[74:77], v[178:181], v[202:205], v[74:77]
	v_mfma_f32_16x16x32_bf16 v[70:73], v[170:173], v[210:213], v[70:73]
	v_mfma_f32_16x16x32_bf16 v[66:69], v[178:181], v[210:213], v[66:69]
	v_mfma_f32_16x16x32_bf16 v[114:117], v[174:177], v[190:193], v[114:117]
	v_mfma_f32_16x16x32_bf16 v[106:109], v[182:185], v[190:193], v[106:109]
	v_mfma_f32_16x16x32_bf16 v[98:101], v[174:177], v[198:201], v[98:101]
	v_mfma_f32_16x16x32_bf16 v[90:93], v[182:185], v[198:201], v[90:93]
	v_mfma_f32_16x16x32_bf16 v[82:85], v[174:177], v[206:209], v[82:85]
	v_mfma_f32_16x16x32_bf16 v[74:77], v[182:185], v[206:209], v[74:77]
	v_mfma_f32_16x16x32_bf16 v[70:73], v[174:177], v[214:217], v[70:73]
	v_mfma_f32_16x16x32_bf16 v[66:69], v[182:185], v[214:217], v[66:69]
	s_setprio 0
	s_barrier
	s_add_i32 s68, s56, s41
	v_lshl_add_u64 v[146:147], s[34:35], 0, v[132:133]
	s_mov_b32 m0, s68
	ds_read_b128 v[186:189], v152 offset:16384
	ds_read_b128 v[190:193], v152 offset:17408
	ds_read_b128 v[194:197], v152 offset:18432
	ds_read_b128 v[198:201], v152 offset:19456
	ds_read_b128 v[202:205], v152 offset:20480
	ds_read_b128 v[206:209], v152 offset:21504
	ds_read_b128 v[210:213], v152 offset:22528
	ds_read_b128 v[214:217], v152 offset:23552
	global_load_lds_dwordx4 v[146:147], off
	s_add_i32 m0, s68, 0x2000
	s_add_u32 s68, s34, 0x100000
	v_lshl_add_u64 v[218:219], s[34:35], 0, v[136:137]
	s_addc_u32 s69, s35, 0
	s_add_i32 s70, s57, s41
	global_load_lds_dwordx4 v[218:219], off
	v_lshl_add_u64 v[220:221], s[68:69], 0, v[132:133]
	s_mov_b32 m0, s70
	v_lshl_add_u64 v[222:223], s[36:37], 0, v[134:135]
	global_load_lds_dwordx4 v[220:221], off
	v_lshl_add_u64 v[220:221], s[68:69], 0, v[136:137]
	s_add_i32 m0, s70, 0x2000
	s_nop 0
	global_load_lds_dwordx4 v[220:221], off
	v_lshl_add_u64 v[220:221], s[36:37], 0, v[130:131]
	s_mov_b32 m0, s29
	s_nop 0
	global_load_lds_dwordx4 v[220:221], off
	s_mov_b32 m0, s44
	s_nop 0
	global_load_lds_dwordx4 v[222:223], off
	s_waitcnt vmcnt(8)
	s_waitcnt lgkmcnt(0)
	s_barrier
	s_setprio 1
	v_mfma_f32_16x16x32_bf16 v[62:65], v[154:157], v[186:189], v[62:65]
	v_mfma_f32_16x16x32_bf16 v[58:61], v[162:165], v[186:189], v[58:61]
	v_mfma_f32_16x16x32_bf16 v[54:57], v[154:157], v[194:197], v[54:57]
	v_mfma_f32_16x16x32_bf16 v[46:49], v[162:165], v[194:197], v[46:49]
	v_mfma_f32_16x16x32_bf16 v[38:41], v[154:157], v[202:205], v[38:41]
	v_mfma_f32_16x16x32_bf16 v[30:33], v[162:165], v[202:205], v[30:33]
	v_mfma_f32_16x16x32_bf16 v[22:25], v[154:157], v[210:213], v[22:25]
	v_mfma_f32_16x16x32_bf16 v[14:17], v[162:165], v[210:213], v[14:17]
	v_mfma_f32_16x16x32_bf16 v[62:65], v[158:161], v[190:193], v[62:65]
	v_mfma_f32_16x16x32_bf16 v[58:61], v[166:169], v[190:193], v[58:61]
	v_mfma_f32_16x16x32_bf16 v[54:57], v[158:161], v[198:201], v[54:57]
	v_mfma_f32_16x16x32_bf16 v[46:49], v[166:169], v[198:201], v[46:49]
	v_mfma_f32_16x16x32_bf16 v[38:41], v[158:161], v[206:209], v[38:41]
	v_mfma_f32_16x16x32_bf16 v[30:33], v[166:169], v[206:209], v[30:33]
	v_mfma_f32_16x16x32_bf16 v[22:25], v[158:161], v[214:217], v[22:25]
	v_mfma_f32_16x16x32_bf16 v[14:17], v[166:169], v[214:217], v[14:17]
	s_setprio 0
	s_setprio 1
	v_mfma_f32_16x16x32_bf16 v[50:53], v[170:173], v[186:189], v[50:53]
	v_mfma_f32_16x16x32_bf16 v[42:45], v[178:181], v[186:189], v[42:45]
	v_mfma_f32_16x16x32_bf16 v[34:37], v[170:173], v[194:197], v[34:37]
	v_mfma_f32_16x16x32_bf16 v[26:29], v[178:181], v[194:197], v[26:29]
	v_mfma_f32_16x16x32_bf16 v[18:21], v[170:173], v[202:205], v[18:21]
	v_mfma_f32_16x16x32_bf16 v[10:13], v[178:181], v[202:205], v[10:13]
	v_mfma_f32_16x16x32_bf16 v[6:9], v[170:173], v[210:213], v[6:9]
	v_mfma_f32_16x16x32_bf16 v[2:5], v[178:181], v[210:213], v[2:5]
	v_mfma_f32_16x16x32_bf16 v[50:53], v[174:177], v[190:193], v[50:53]
	v_mfma_f32_16x16x32_bf16 v[42:45], v[182:185], v[190:193], v[42:45]
	v_mfma_f32_16x16x32_bf16 v[34:37], v[174:177], v[198:201], v[34:37]
	v_mfma_f32_16x16x32_bf16 v[26:29], v[182:185], v[198:201], v[26:29]
	v_mfma_f32_16x16x32_bf16 v[18:21], v[174:177], v[206:209], v[18:21]
	v_mfma_f32_16x16x32_bf16 v[10:13], v[182:185], v[206:209], v[10:13]
	v_mfma_f32_16x16x32_bf16 v[6:9], v[174:177], v[214:217], v[6:9]
	v_mfma_f32_16x16x32_bf16 v[2:5], v[182:185], v[214:217], v[2:5]
	s_setprio 0
	s_barrier
	s_add_i32 s68, 0, 0x18000
	v_add_u32_e32 v153, s68, v148
	s_add_i32 s69, 0, 0x1c000
	ds_read_b128 v[154:157], v153
	ds_read_b128 v[158:161], v153 offset:1024
	ds_read_b128 v[162:165], v153 offset:2048
	ds_read_b128 v[166:169], v153 offset:3072
	v_add_u32_e32 v153, s69, v148
	ds_read_b128 v[170:173], v153
	ds_read_b128 v[174:177], v153 offset:1024
	ds_read_b128 v[178:181], v153 offset:2048
	ds_read_b128 v[182:185], v153 offset:3072
	s_add_u32 s36, s36, 0x100000
	s_addc_u32 s37, s37, 0
	s_mov_b32 m0, s45
	v_lshl_add_u64 v[224:225], s[36:37], 0, v[130:131]
	ds_read_b128 v[186:189], v152 offset:32768
	ds_read_b128 v[190:193], v152 offset:33792
	ds_read_b128 v[194:197], v152 offset:34816
	ds_read_b128 v[198:201], v152 offset:35840
	ds_read_b128 v[202:205], v152 offset:36864
	ds_read_b128 v[206:209], v152 offset:37888
	ds_read_b128 v[210:213], v152 offset:38912
	ds_read_b128 v[214:217], v152 offset:39936
	global_load_lds_dwordx4 v[224:225], off
	v_lshl_add_u64 v[224:225], s[36:37], 0, v[134:135]
	s_mov_b32 m0, s46
	s_nop 0
	global_load_lds_dwordx4 v[224:225], off
	s_waitcnt vmcnt(8)
	s_waitcnt lgkmcnt(0)
	s_barrier
	s_setprio 1
	v_mfma_f32_16x16x32_bf16 v[126:129], v[154:157], v[186:189], v[126:129]
	v_mfma_f32_16x16x32_bf16 v[122:125], v[162:165], v[186:189], v[122:125]
	v_mfma_f32_16x16x32_bf16 v[118:121], v[154:157], v[194:197], v[118:121]
	v_mfma_f32_16x16x32_bf16 v[110:113], v[162:165], v[194:197], v[110:113]
	v_mfma_f32_16x16x32_bf16 v[102:105], v[154:157], v[202:205], v[102:105]
	v_mfma_f32_16x16x32_bf16 v[94:97], v[162:165], v[202:205], v[94:97]
	v_mfma_f32_16x16x32_bf16 v[86:89], v[154:157], v[210:213], v[86:89]
	v_mfma_f32_16x16x32_bf16 v[78:81], v[162:165], v[210:213], v[78:81]
	v_mfma_f32_16x16x32_bf16 v[126:129], v[158:161], v[190:193], v[126:129]
	v_mfma_f32_16x16x32_bf16 v[122:125], v[166:169], v[190:193], v[122:125]
	v_mfma_f32_16x16x32_bf16 v[118:121], v[158:161], v[198:201], v[118:121]
	v_mfma_f32_16x16x32_bf16 v[110:113], v[166:169], v[198:201], v[110:113]
	v_mfma_f32_16x16x32_bf16 v[102:105], v[158:161], v[206:209], v[102:105]
	v_mfma_f32_16x16x32_bf16 v[94:97], v[166:169], v[206:209], v[94:97]
	v_mfma_f32_16x16x32_bf16 v[86:89], v[158:161], v[214:217], v[86:89]
	v_mfma_f32_16x16x32_bf16 v[78:81], v[166:169], v[214:217], v[78:81]
	s_setprio 0
	s_setprio 1
	v_mfma_f32_16x16x32_bf16 v[114:117], v[170:173], v[186:189], v[114:117]
	v_mfma_f32_16x16x32_bf16 v[106:109], v[178:181], v[186:189], v[106:109]
	v_mfma_f32_16x16x32_bf16 v[98:101], v[170:173], v[194:197], v[98:101]
	v_mfma_f32_16x16x32_bf16 v[90:93], v[178:181], v[194:197], v[90:93]
	v_mfma_f32_16x16x32_bf16 v[82:85], v[170:173], v[202:205], v[82:85]
	v_mfma_f32_16x16x32_bf16 v[74:77], v[178:181], v[202:205], v[74:77]
	v_mfma_f32_16x16x32_bf16 v[70:73], v[170:173], v[210:213], v[70:73]
	v_mfma_f32_16x16x32_bf16 v[66:69], v[178:181], v[210:213], v[66:69]
	v_mfma_f32_16x16x32_bf16 v[114:117], v[174:177], v[190:193], v[114:117]
	v_mfma_f32_16x16x32_bf16 v[106:109], v[182:185], v[190:193], v[106:109]
	v_mfma_f32_16x16x32_bf16 v[98:101], v[174:177], v[198:201], v[98:101]
	v_mfma_f32_16x16x32_bf16 v[90:93], v[182:185], v[198:201], v[90:93]
	v_mfma_f32_16x16x32_bf16 v[82:85], v[174:177], v[206:209], v[82:85]
	v_mfma_f32_16x16x32_bf16 v[74:77], v[182:185], v[206:209], v[74:77]
	v_mfma_f32_16x16x32_bf16 v[70:73], v[174:177], v[214:217], v[70:73]
	v_mfma_f32_16x16x32_bf16 v[66:69], v[182:185], v[214:217], v[66:69]
	s_setprio 0
	s_barrier
	s_add_i32 s36, s68, s41
	v_lshl_add_u64 v[146:147], v[146:147], 0, s[8:9]
	s_mov_b32 m0, s36
	ds_read_b128 v[186:189], v152 offset:49152
	ds_read_b128 v[190:193], v152 offset:50176
	ds_read_b128 v[194:197], v152 offset:51200
	ds_read_b128 v[198:201], v152 offset:52224
	ds_read_b128 v[202:205], v152 offset:53248
	ds_read_b128 v[206:209], v152 offset:54272
	ds_read_b128 v[210:213], v152 offset:55296
	ds_read_b128 v[214:217], v152 offset:56320
	global_load_lds_dwordx4 v[146:147], off
	s_add_i32 m0, s36, 0x2000
	s_add_u32 s34, s34, 0x100080
	v_lshl_add_u64 v[146:147], v[218:219], 0, s[8:9]
	s_addc_u32 s35, s35, 0
	s_add_i32 s36, s69, s41
	global_load_lds_dwordx4 v[146:147], off
	v_lshl_add_u64 v[146:147], s[34:35], 0, v[132:133]
	s_mov_b32 m0, s36
	s_nop 0
	global_load_lds_dwordx4 v[146:147], off
	v_lshl_add_u64 v[146:147], s[34:35], 0, v[136:137]
	s_add_i32 m0, s36, 0x2000
	s_nop 0
	global_load_lds_dwordx4 v[146:147], off
	v_lshl_add_u64 v[146:147], v[220:221], 0, s[8:9]
	s_mov_b32 m0, s52
	s_nop 0
	global_load_lds_dwordx4 v[146:147], off
	v_lshl_add_u64 v[146:147], v[222:223], 0, s[8:9]
	s_mov_b32 m0, s53
	s_nop 0
	global_load_lds_dwordx4 v[146:147], off
	s_waitcnt vmcnt(8)
	s_waitcnt lgkmcnt(0)
	s_barrier
	s_add_i32 s67, s67, 2
	s_add_u32 s30, s30, 0x100
	s_addc_u32 s31, s31, 0
	s_add_u32 s65, s65, 0x100
	s_addc_u32 s66, s66, 0
	s_cmp_gt_u32 s67, 61
	s_setprio 1
	s_waitcnt lgkmcnt(0)
	v_mfma_f32_16x16x32_bf16 v[62:65], v[154:157], v[186:189], v[62:65]
	v_mfma_f32_16x16x32_bf16 v[58:61], v[162:165], v[186:189], v[58:61]
	v_mfma_f32_16x16x32_bf16 v[54:57], v[154:157], v[194:197], v[54:57]
	v_mfma_f32_16x16x32_bf16 v[46:49], v[162:165], v[194:197], v[46:49]
	v_mfma_f32_16x16x32_bf16 v[38:41], v[154:157], v[202:205], v[38:41]
	v_mfma_f32_16x16x32_bf16 v[30:33], v[162:165], v[202:205], v[30:33]
	v_mfma_f32_16x16x32_bf16 v[22:25], v[154:157], v[210:213], v[22:25]
	v_mfma_f32_16x16x32_bf16 v[14:17], v[162:165], v[210:213], v[14:17]
	v_mfma_f32_16x16x32_bf16 v[62:65], v[158:161], v[190:193], v[62:65]
	v_mfma_f32_16x16x32_bf16 v[58:61], v[166:169], v[190:193], v[58:61]
	v_mfma_f32_16x16x32_bf16 v[54:57], v[158:161], v[198:201], v[54:57]
	v_mfma_f32_16x16x32_bf16 v[46:49], v[166:169], v[198:201], v[46:49]
	v_mfma_f32_16x16x32_bf16 v[38:41], v[158:161], v[206:209], v[38:41]
	v_mfma_f32_16x16x32_bf16 v[30:33], v[166:169], v[206:209], v[30:33]
	v_mfma_f32_16x16x32_bf16 v[22:25], v[158:161], v[214:217], v[22:25]
	v_mfma_f32_16x16x32_bf16 v[14:17], v[166:169], v[214:217], v[14:17]
	s_setprio 0
	s_setprio 1
	v_mfma_f32_16x16x32_bf16 v[50:53], v[170:173], v[186:189], v[50:53]
	v_mfma_f32_16x16x32_bf16 v[42:45], v[178:181], v[186:189], v[42:45]
	v_mfma_f32_16x16x32_bf16 v[34:37], v[170:173], v[194:197], v[34:37]
	v_mfma_f32_16x16x32_bf16 v[26:29], v[178:181], v[194:197], v[26:29]
	v_mfma_f32_16x16x32_bf16 v[18:21], v[170:173], v[202:205], v[18:21]
	v_mfma_f32_16x16x32_bf16 v[10:13], v[178:181], v[202:205], v[10:13]
	v_mfma_f32_16x16x32_bf16 v[6:9], v[170:173], v[210:213], v[6:9]
	v_mfma_f32_16x16x32_bf16 v[2:5], v[178:181], v[210:213], v[2:5]
	v_mfma_f32_16x16x32_bf16 v[50:53], v[174:177], v[190:193], v[50:53]
	v_mfma_f32_16x16x32_bf16 v[42:45], v[182:185], v[190:193], v[42:45]
	v_mfma_f32_16x16x32_bf16 v[34:37], v[174:177], v[198:201], v[34:37]
	v_mfma_f32_16x16x32_bf16 v[26:29], v[182:185], v[198:201], v[26:29]
	v_mfma_f32_16x16x32_bf16 v[18:21], v[174:177], v[206:209], v[18:21]
	v_mfma_f32_16x16x32_bf16 v[10:13], v[182:185], v[206:209], v[10:13]
	v_mfma_f32_16x16x32_bf16 v[6:9], v[174:177], v[214:217], v[6:9]
	v_mfma_f32_16x16x32_bf16 v[2:5], v[182:185], v[214:217], v[2:5]
	s_setprio 0
	s_barrier
	s_cbranch_scc0 .LBB0_728
	s_and_b64 vcc, exec, s[10:11]
	s_cbranch_vccz .LBB0_731
	s_barrier

.LBB0_855:
	ds_read_b128 v[146:149], v152
	ds_read_b128 v[156:159], v152 offset:1024
	ds_read_b128 v[160:163], v152 offset:2048
	ds_read_b128 v[164:167], v152 offset:3072
	ds_read_b128 v[168:171], v153
	ds_read_b128 v[172:175], v153 offset:1024
	ds_read_b128 v[176:179], v153 offset:2048
	ds_read_b128 v[180:183], v153 offset:3072
	s_add_u32 s24, s22, 0xfffc0080
	s_addc_u32 s25, s23, -1
	s_cmp_eq_u32 s57, 12
	s_cselect_b32 s27, s15, s25
	s_cselect_b32 s26, s53, s24
	s_cselect_b32 s25, s13, s56
	s_cselect_b32 s24, s54, s55
	v_lshl_add_u64 v[216:217], s[22:23], 0, v[138:139]
	s_add_i32 m0, s21, 0xc000
	ds_read_b128 v[184:187], v154
	ds_read_b128 v[188:191], v154 offset:1024
	ds_read_b128 v[192:195], v154 offset:2048
	ds_read_b128 v[196:199], v154 offset:3072
	ds_read_b128 v[200:203], v154 offset:4096
	ds_read_b128 v[204:207], v154 offset:5120
	ds_read_b128 v[208:211], v154 offset:6144
	ds_read_b128 v[212:215], v154 offset:7168
	global_load_lds_dwordx4 v[216:217], off
	v_lshl_add_u64 v[216:217], s[22:23], 0, v[140:141]
	s_add_i32 m0, s21, 0xe000
	s_nop 0
	global_load_lds_dwordx4 v[216:217], off
	s_waitcnt vmcnt(8)
	s_waitcnt lgkmcnt(0)
	s_barrier
	s_setprio 1
	v_mfma_f32_16x16x32_bf16 v[126:129], v[146:149], v[184:187], v[126:129]
	v_mfma_f32_16x16x32_bf16 v[122:125], v[160:163], v[184:187], v[122:125]
	v_mfma_f32_16x16x32_bf16 v[118:121], v[146:149], v[192:195], v[118:121]
	v_mfma_f32_16x16x32_bf16 v[110:113], v[160:163], v[192:195], v[110:113]
	v_mfma_f32_16x16x32_bf16 v[102:105], v[146:149], v[200:203], v[102:105]
	v_mfma_f32_16x16x32_bf16 v[94:97], v[160:163], v[200:203], v[94:97]
	v_mfma_f32_16x16x32_bf16 v[86:89], v[146:149], v[208:211], v[86:89]
	v_mfma_f32_16x16x32_bf16 v[78:81], v[160:163], v[208:211], v[78:81]
	v_mfma_f32_16x16x32_bf16 v[126:129], v[156:159], v[188:191], v[126:129]
	v_mfma_f32_16x16x32_bf16 v[122:125], v[164:167], v[188:191], v[122:125]
	v_mfma_f32_16x16x32_bf16 v[118:121], v[156:159], v[196:199], v[118:121]
	v_mfma_f32_16x16x32_bf16 v[110:113], v[164:167], v[196:199], v[110:113]
	v_mfma_f32_16x16x32_bf16 v[102:105], v[156:159], v[204:207], v[102:105]
	v_mfma_f32_16x16x32_bf16 v[94:97], v[164:167], v[204:207], v[94:97]
	v_mfma_f32_16x16x32_bf16 v[86:89], v[156:159], v[212:215], v[86:89]
	v_mfma_f32_16x16x32_bf16 v[78:81], v[164:167], v[212:215], v[78:81]
	s_setprio 0
	s_setprio 1
	v_mfma_f32_16x16x32_bf16 v[114:117], v[168:171], v[184:187], v[114:117]
	v_mfma_f32_16x16x32_bf16 v[106:109], v[176:179], v[184:187], v[106:109]
	v_mfma_f32_16x16x32_bf16 v[98:101], v[168:171], v[192:195], v[98:101]
	v_mfma_f32_16x16x32_bf16 v[90:93], v[176:179], v[192:195], v[90:93]
	v_mfma_f32_16x16x32_bf16 v[82:85], v[168:171], v[200:203], v[82:85]
	v_mfma_f32_16x16x32_bf16 v[74:77], v[176:179], v[200:203], v[74:77]
	v_mfma_f32_16x16x32_bf16 v[70:73], v[168:171], v[208:211], v[70:73]
	v_mfma_f32_16x16x32_bf16 v[66:69], v[176:179], v[208:211], v[66:69]
	v_mfma_f32_16x16x32_bf16 v[114:117], v[172:175], v[188:191], v[114:117]
	v_mfma_f32_16x16x32_bf16 v[106:109], v[180:183], v[188:191], v[106:109]
	v_mfma_f32_16x16x32_bf16 v[98:101], v[172:175], v[196:199], v[98:101]
	v_mfma_f32_16x16x32_bf16 v[90:93], v[180:183], v[196:199], v[90:93]
	v_mfma_f32_16x16x32_bf16 v[82:85], v[172:175], v[204:207], v[82:85]
	v_mfma_f32_16x16x32_bf16 v[74:77], v[180:183], v[204:207], v[74:77]
	v_mfma_f32_16x16x32_bf16 v[70:73], v[172:175], v[212:215], v[70:73]
	v_mfma_f32_16x16x32_bf16 v[66:69], v[180:183], v[212:215], v[66:69]
	s_setprio 0
	s_barrier
	s_add_i32 s58, s45, s31
	v_lshl_add_u64 v[216:217], s[24:25], 0, v[134:135]
	s_mov_b32 m0, s58
	ds_read_b128 v[184:187], v154 offset:16384
	ds_read_b128 v[188:191], v154 offset:17408
	ds_read_b128 v[192:195], v154 offset:18432
	ds_read_b128 v[196:199], v154 offset:19456
	ds_read_b128 v[200:203], v154 offset:20480
	ds_read_b128 v[204:207], v154 offset:21504
	ds_read_b128 v[208:211], v154 offset:22528
	ds_read_b128 v[212:215], v154 offset:23552
	global_load_lds_dwordx4 v[216:217], off
	s_add_i32 m0, s58, 0x2000
	s_add_u32 s58, s24, 0x40000
	v_lshl_add_u64 v[218:219], s[24:25], 0, v[130:131]
	s_addc_u32 s59, s25, 0
	s_add_i32 s60, s46, s31
	global_load_lds_dwordx4 v[218:219], off
	v_lshl_add_u64 v[220:221], s[58:59], 0, v[134:135]
	s_mov_b32 m0, s60
	v_lshl_add_u64 v[222:223], s[26:27], 0, v[132:133]
	global_load_lds_dwordx4 v[220:221], off
	v_lshl_add_u64 v[220:221], s[58:59], 0, v[130:131]
	s_add_i32 m0, s60, 0x2000
	s_nop 0
	global_load_lds_dwordx4 v[220:221], off
	v_lshl_add_u64 v[220:221], s[26:27], 0, v[136:137]
	s_mov_b32 m0, s21
	s_nop 0
	global_load_lds_dwordx4 v[220:221], off
	s_mov_b32 m0, s35
	s_nop 0
	global_load_lds_dwordx4 v[222:223], off
	s_waitcnt vmcnt(8)
	s_waitcnt lgkmcnt(0)
	s_barrier
	s_setprio 1
	v_mfma_f32_16x16x32_bf16 v[62:65], v[146:149], v[184:187], v[62:65]
	v_mfma_f32_16x16x32_bf16 v[58:61], v[160:163], v[184:187], v[58:61]
	v_mfma_f32_16x16x32_bf16 v[54:57], v[146:149], v[192:195], v[54:57]
	v_mfma_f32_16x16x32_bf16 v[46:49], v[160:163], v[192:195], v[46:49]
	v_mfma_f32_16x16x32_bf16 v[38:41], v[146:149], v[200:203], v[38:41]
	v_mfma_f32_16x16x32_bf16 v[30:33], v[160:163], v[200:203], v[30:33]
	v_mfma_f32_16x16x32_bf16 v[22:25], v[146:149], v[208:211], v[22:25]
	v_mfma_f32_16x16x32_bf16 v[14:17], v[160:163], v[208:211], v[14:17]
	v_mfma_f32_16x16x32_bf16 v[62:65], v[156:159], v[188:191], v[62:65]
	v_mfma_f32_16x16x32_bf16 v[58:61], v[164:167], v[188:191], v[58:61]
	v_mfma_f32_16x16x32_bf16 v[54:57], v[156:159], v[196:199], v[54:57]
	v_mfma_f32_16x16x32_bf16 v[46:49], v[164:167], v[196:199], v[46:49]
	v_mfma_f32_16x16x32_bf16 v[38:41], v[156:159], v[204:207], v[38:41]
	v_mfma_f32_16x16x32_bf16 v[30:33], v[164:167], v[204:207], v[30:33]
	v_mfma_f32_16x16x32_bf16 v[22:25], v[156:159], v[212:215], v[22:25]
	v_mfma_f32_16x16x32_bf16 v[14:17], v[164:167], v[212:215], v[14:17]
	s_setprio 0
	s_setprio 1
	v_mfma_f32_16x16x32_bf16 v[50:53], v[168:171], v[184:187], v[50:53]
	v_mfma_f32_16x16x32_bf16 v[42:45], v[176:179], v[184:187], v[42:45]
	v_mfma_f32_16x16x32_bf16 v[34:37], v[168:171], v[192:195], v[34:37]
	v_mfma_f32_16x16x32_bf16 v[26:29], v[176:179], v[192:195], v[26:29]
	v_mfma_f32_16x16x32_bf16 v[18:21], v[168:171], v[200:203], v[18:21]
	v_mfma_f32_16x16x32_bf16 v[10:13], v[176:179], v[200:203], v[10:13]
	v_mfma_f32_16x16x32_bf16 v[6:9], v[168:171], v[208:211], v[6:9]
	v_mfma_f32_16x16x32_bf16 v[2:5], v[176:179], v[208:211], v[2:5]
	v_mfma_f32_16x16x32_bf16 v[50:53], v[172:175], v[188:191], v[50:53]
	v_mfma_f32_16x16x32_bf16 v[42:45], v[180:183], v[188:191], v[42:45]
	v_mfma_f32_16x16x32_bf16 v[34:37], v[172:175], v[196:199], v[34:37]
	v_mfma_f32_16x16x32_bf16 v[26:29], v[180:183], v[196:199], v[26:29]
	v_mfma_f32_16x16x32_bf16 v[18:21], v[172:175], v[204:207], v[18:21]
	v_mfma_f32_16x16x32_bf16 v[10:13], v[180:183], v[204:207], v[10:13]
	v_mfma_f32_16x16x32_bf16 v[6:9], v[172:175], v[212:215], v[6:9]
	v_mfma_f32_16x16x32_bf16 v[2:5], v[180:183], v[212:215], v[2:5]
	s_setprio 0
	s_barrier
	s_add_i32 s58, 0, 0x18000
	v_add_u32_e32 v155, s58, v150
	s_add_i32 s59, 0, 0x1c000
	ds_read_b128 v[146:149], v155
	ds_read_b128 v[156:159], v155 offset:1024
	ds_read_b128 v[160:163], v155 offset:2048
	ds_read_b128 v[164:167], v155 offset:3072
	v_add_u32_e32 v155, s59, v150
	ds_read_b128 v[168:171], v155
	ds_read_b128 v[172:175], v155 offset:1024
	ds_read_b128 v[176:179], v155 offset:2048
	ds_read_b128 v[180:183], v155 offset:3072
	s_add_u32 s26, s26, 0x40000
	s_addc_u32 s27, s27, 0
	s_mov_b32 m0, s36
	v_lshl_add_u64 v[224:225], s[26:27], 0, v[136:137]
	ds_read_b128 v[184:187], v154 offset:32768
	ds_read_b128 v[188:191], v154 offset:33792
	ds_read_b128 v[192:195], v154 offset:34816
	ds_read_b128 v[196:199], v154 offset:35840
	ds_read_b128 v[200:203], v154 offset:36864
	ds_read_b128 v[204:207], v154 offset:37888
	ds_read_b128 v[208:211], v154 offset:38912
	ds_read_b128 v[212:215], v154 offset:39936
	global_load_lds_dwordx4 v[224:225], off
	v_lshl_add_u64 v[224:225], s[26:27], 0, v[132:133]
	s_mov_b32 m0, s37
	s_nop 0
	global_load_lds_dwordx4 v[224:225], off
	s_waitcnt vmcnt(8)
	s_waitcnt lgkmcnt(0)
	s_barrier
	s_setprio 1
	v_mfma_f32_16x16x32_bf16 v[126:129], v[146:149], v[184:187], v[126:129]
	v_mfma_f32_16x16x32_bf16 v[122:125], v[160:163], v[184:187], v[122:125]
	v_mfma_f32_16x16x32_bf16 v[118:121], v[146:149], v[192:195], v[118:121]
	v_mfma_f32_16x16x32_bf16 v[110:113], v[160:163], v[192:195], v[110:113]
	v_mfma_f32_16x16x32_bf16 v[102:105], v[146:149], v[200:203], v[102:105]
	v_mfma_f32_16x16x32_bf16 v[94:97], v[160:163], v[200:203], v[94:97]
	v_mfma_f32_16x16x32_bf16 v[86:89], v[146:149], v[208:211], v[86:89]
	v_mfma_f32_16x16x32_bf16 v[78:81], v[160:163], v[208:211], v[78:81]
	v_mfma_f32_16x16x32_bf16 v[126:129], v[156:159], v[188:191], v[126:129]
	v_mfma_f32_16x16x32_bf16 v[122:125], v[164:167], v[188:191], v[122:125]
	v_mfma_f32_16x16x32_bf16 v[118:121], v[156:159], v[196:199], v[118:121]
	v_mfma_f32_16x16x32_bf16 v[110:113], v[164:167], v[196:199], v[110:113]
	v_mfma_f32_16x16x32_bf16 v[102:105], v[156:159], v[204:207], v[102:105]
	v_mfma_f32_16x16x32_bf16 v[94:97], v[164:167], v[204:207], v[94:97]
	v_mfma_f32_16x16x32_bf16 v[86:89], v[156:159], v[212:215], v[86:89]
	v_mfma_f32_16x16x32_bf16 v[78:81], v[164:167], v[212:215], v[78:81]
	s_setprio 0
	s_setprio 1
	v_mfma_f32_16x16x32_bf16 v[114:117], v[168:171], v[184:187], v[114:117]
	v_mfma_f32_16x16x32_bf16 v[106:109], v[176:179], v[184:187], v[106:109]
	v_mfma_f32_16x16x32_bf16 v[98:101], v[168:171], v[192:195], v[98:101]
	v_mfma_f32_16x16x32_bf16 v[90:93], v[176:179], v[192:195], v[90:93]
	v_mfma_f32_16x16x32_bf16 v[82:85], v[168:171], v[200:203], v[82:85]
	v_mfma_f32_16x16x32_bf16 v[74:77], v[176:179], v[200:203], v[74:77]
	v_mfma_f32_16x16x32_bf16 v[70:73], v[168:171], v[208:211], v[70:73]
	v_mfma_f32_16x16x32_bf16 v[66:69], v[176:179], v[208:211], v[66:69]
	v_mfma_f32_16x16x32_bf16 v[114:117], v[172:175], v[188:191], v[114:117]
	v_mfma_f32_16x16x32_bf16 v[106:109], v[180:183], v[188:191], v[106:109]
	v_mfma_f32_16x16x32_bf16 v[98:101], v[172:175], v[196:199], v[98:101]
	v_mfma_f32_16x16x32_bf16 v[90:93], v[180:183], v[196:199], v[90:93]
	v_mfma_f32_16x16x32_bf16 v[82:85], v[172:175], v[204:207], v[82:85]
	v_mfma_f32_16x16x32_bf16 v[74:77], v[180:183], v[204:207], v[74:77]
	v_mfma_f32_16x16x32_bf16 v[70:73], v[172:175], v[212:215], v[70:73]
	v_mfma_f32_16x16x32_bf16 v[66:69], v[180:183], v[212:215], v[66:69]
	s_setprio 0
	s_barrier
	s_add_i32 s26, s58, s31
	v_lshl_add_u64 v[216:217], v[216:217], 0, s[8:9]
	s_mov_b32 m0, s26
	ds_read_b128 v[184:187], v154 offset:49152
	ds_read_b128 v[188:191], v154 offset:50176
	ds_read_b128 v[192:195], v154 offset:51200
	ds_read_b128 v[196:199], v154 offset:52224
	ds_read_b128 v[200:203], v154 offset:53248
	ds_read_b128 v[204:207], v154 offset:54272
	ds_read_b128 v[208:211], v154 offset:55296
	ds_read_b128 v[212:215], v154 offset:56320
	global_load_lds_dwordx4 v[216:217], off
	s_add_i32 m0, s26, 0x2000
	s_add_u32 s24, s24, 0x40080
	v_lshl_add_u64 v[216:217], v[218:219], 0, s[8:9]
	s_addc_u32 s25, s25, 0
	s_add_i32 s26, s59, s31
	global_load_lds_dwordx4 v[216:217], off
	v_lshl_add_u64 v[216:217], s[24:25], 0, v[134:135]
	s_mov_b32 m0, s26
	s_nop 0
	global_load_lds_dwordx4 v[216:217], off
	v_lshl_add_u64 v[216:217], s[24:25], 0, v[130:131]
	s_add_i32 m0, s26, 0x2000
	s_nop 0
	global_load_lds_dwordx4 v[216:217], off
	v_lshl_add_u64 v[216:217], v[220:221], 0, s[8:9]
	s_mov_b32 m0, s39
	s_nop 0
	global_load_lds_dwordx4 v[216:217], off
	v_lshl_add_u64 v[216:217], v[222:223], 0, s[8:9]
	s_mov_b32 m0, s40
	s_nop 0
	global_load_lds_dwordx4 v[216:217], off
	s_waitcnt vmcnt(8)
	s_waitcnt lgkmcnt(0)
	s_barrier
	s_add_i32 s57, s57, 2
	s_add_u32 s22, s22, 0x100
	s_addc_u32 s23, s23, 0
	s_add_u32 s55, s55, 0x100
	s_addc_u32 s56, s56, 0
	s_cmp_gt_u32 s57, 13
	s_setprio 1
	s_waitcnt lgkmcnt(0)
	v_mfma_f32_16x16x32_bf16 v[62:65], v[146:149], v[184:187], v[62:65]
	v_mfma_f32_16x16x32_bf16 v[58:61], v[160:163], v[184:187], v[58:61]
	v_mfma_f32_16x16x32_bf16 v[54:57], v[146:149], v[192:195], v[54:57]
	v_mfma_f32_16x16x32_bf16 v[46:49], v[160:163], v[192:195], v[46:49]
	v_mfma_f32_16x16x32_bf16 v[38:41], v[146:149], v[200:203], v[38:41]
	v_mfma_f32_16x16x32_bf16 v[30:33], v[160:163], v[200:203], v[30:33]
	v_mfma_f32_16x16x32_bf16 v[22:25], v[146:149], v[208:211], v[22:25]
	v_mfma_f32_16x16x32_bf16 v[14:17], v[160:163], v[208:211], v[14:17]
	v_mfma_f32_16x16x32_bf16 v[62:65], v[156:159], v[188:191], v[62:65]
	v_mfma_f32_16x16x32_bf16 v[58:61], v[164:167], v[188:191], v[58:61]
	v_mfma_f32_16x16x32_bf16 v[54:57], v[156:159], v[196:199], v[54:57]
	v_mfma_f32_16x16x32_bf16 v[46:49], v[164:167], v[196:199], v[46:49]
	v_mfma_f32_16x16x32_bf16 v[38:41], v[156:159], v[204:207], v[38:41]
	v_mfma_f32_16x16x32_bf16 v[30:33], v[164:167], v[204:207], v[30:33]
	v_mfma_f32_16x16x32_bf16 v[22:25], v[156:159], v[212:215], v[22:25]
	v_mfma_f32_16x16x32_bf16 v[14:17], v[164:167], v[212:215], v[14:17]
	s_setprio 0
	s_setprio 1
	v_mfma_f32_16x16x32_bf16 v[50:53], v[168:171], v[184:187], v[50:53]
	v_mfma_f32_16x16x32_bf16 v[42:45], v[176:179], v[184:187], v[42:45]
	v_mfma_f32_16x16x32_bf16 v[34:37], v[168:171], v[192:195], v[34:37]
	v_mfma_f32_16x16x32_bf16 v[26:29], v[176:179], v[192:195], v[26:29]
	v_mfma_f32_16x16x32_bf16 v[18:21], v[168:171], v[200:203], v[18:21]
	v_mfma_f32_16x16x32_bf16 v[10:13], v[176:179], v[200:203], v[10:13]
	v_mfma_f32_16x16x32_bf16 v[6:9], v[168:171], v[208:211], v[6:9]
	v_mfma_f32_16x16x32_bf16 v[2:5], v[176:179], v[208:211], v[2:5]
	v_mfma_f32_16x16x32_bf16 v[50:53], v[172:175], v[188:191], v[50:53]
	v_mfma_f32_16x16x32_bf16 v[42:45], v[180:183], v[188:191], v[42:45]
	v_mfma_f32_16x16x32_bf16 v[34:37], v[172:175], v[196:199], v[34:37]
	v_mfma_f32_16x16x32_bf16 v[26:29], v[180:183], v[196:199], v[26:29]
	v_mfma_f32_16x16x32_bf16 v[18:21], v[172:175], v[204:207], v[18:21]
	v_mfma_f32_16x16x32_bf16 v[10:13], v[180:183], v[204:207], v[10:13]
	v_mfma_f32_16x16x32_bf16 v[6:9], v[172:175], v[212:215], v[6:9]
	v_mfma_f32_16x16x32_bf16 v[2:5], v[180:183], v[212:215], v[2:5]
	s_setprio 0
	s_barrier
	s_cbranch_scc0 .LBB0_855
	s_and_b64 vcc, exec, s[10:11]
	s_cbranch_vccz .LBB0_858
	s_barrier

.LBB0_1031:
	ds_read_b128 v[154:157], v150
	ds_read_b128 v[158:161], v150 offset:1024
	ds_read_b128 v[162:165], v150 offset:2048
	ds_read_b128 v[166:169], v150 offset:3072
	ds_read_b128 v[170:173], v151
	ds_read_b128 v[174:177], v151 offset:1024
	ds_read_b128 v[178:181], v151 offset:2048
	ds_read_b128 v[182:185], v151 offset:3072
	s_add_u32 s34, s30, 0xfffc0080
	s_addc_u32 s35, s31, -1
	s_cmp_eq_u32 s65, 12
	s_cselect_b32 s37, s23, s35
	s_cselect_b32 s36, s61, s34
	s_cselect_b32 s35, s21, s64
	s_cselect_b32 s34, s62, s63
	v_lshl_add_u64 v[146:147], s[30:31], 0, v[138:139]
	s_add_i32 m0, s29, 0xc000
	ds_read_b128 v[186:189], v152
	ds_read_b128 v[190:193], v152 offset:1024
	ds_read_b128 v[194:197], v152 offset:2048
	ds_read_b128 v[198:201], v152 offset:3072
	ds_read_b128 v[202:205], v152 offset:4096
	ds_read_b128 v[206:209], v152 offset:5120
	ds_read_b128 v[210:213], v152 offset:6144
	ds_read_b128 v[214:217], v152 offset:7168
	global_load_lds_dwordx4 v[146:147], off
	v_lshl_add_u64 v[146:147], s[30:31], 0, v[140:141]
	s_add_i32 m0, s29, 0xe000
	s_nop 0
	global_load_lds_dwordx4 v[146:147], off
	s_waitcnt vmcnt(8)
	s_waitcnt lgkmcnt(0)
	s_barrier
	s_setprio 1
	v_mfma_f32_16x16x32_bf16 v[126:129], v[154:157], v[186:189], v[126:129]
	v_mfma_f32_16x16x32_bf16 v[122:125], v[162:165], v[186:189], v[122:125]
	v_mfma_f32_16x16x32_bf16 v[118:121], v[154:157], v[194:197], v[118:121]
	v_mfma_f32_16x16x32_bf16 v[110:113], v[162:165], v[194:197], v[110:113]
	v_mfma_f32_16x16x32_bf16 v[102:105], v[154:157], v[202:205], v[102:105]
	v_mfma_f32_16x16x32_bf16 v[94:97], v[162:165], v[202:205], v[94:97]
	v_mfma_f32_16x16x32_bf16 v[86:89], v[154:157], v[210:213], v[86:89]
	v_mfma_f32_16x16x32_bf16 v[78:81], v[162:165], v[210:213], v[78:81]
	v_mfma_f32_16x16x32_bf16 v[126:129], v[158:161], v[190:193], v[126:129]
	v_mfma_f32_16x16x32_bf16 v[122:125], v[166:169], v[190:193], v[122:125]
	v_mfma_f32_16x16x32_bf16 v[118:121], v[158:161], v[198:201], v[118:121]
	v_mfma_f32_16x16x32_bf16 v[110:113], v[166:169], v[198:201], v[110:113]
	v_mfma_f32_16x16x32_bf16 v[102:105], v[158:161], v[206:209], v[102:105]
	v_mfma_f32_16x16x32_bf16 v[94:97], v[166:169], v[206:209], v[94:97]
	v_mfma_f32_16x16x32_bf16 v[86:89], v[158:161], v[214:217], v[86:89]
	v_mfma_f32_16x16x32_bf16 v[78:81], v[166:169], v[214:217], v[78:81]
	s_setprio 0
	s_setprio 1
	v_mfma_f32_16x16x32_bf16 v[114:117], v[170:173], v[186:189], v[114:117]
	v_mfma_f32_16x16x32_bf16 v[106:109], v[178:181], v[186:189], v[106:109]
	v_mfma_f32_16x16x32_bf16 v[98:101], v[170:173], v[194:197], v[98:101]
	v_mfma_f32_16x16x32_bf16 v[90:93], v[178:181], v[194:197], v[90:93]
	v_mfma_f32_16x16x32_bf16 v[82:85], v[170:173], v[202:205], v[82:85]
	v_mfma_f32_16x16x32_bf16 v[74:77], v[178:181], v[202:205], v[74:77]
	v_mfma_f32_16x16x32_bf16 v[70:73], v[170:173], v[210:213], v[70:73]
	v_mfma_f32_16x16x32_bf16 v[66:69], v[178:181], v[210:213], v[66:69]
	v_mfma_f32_16x16x32_bf16 v[114:117], v[174:177], v[190:193], v[114:117]
	v_mfma_f32_16x16x32_bf16 v[106:109], v[182:185], v[190:193], v[106:109]
	v_mfma_f32_16x16x32_bf16 v[98:101], v[174:177], v[198:201], v[98:101]
	v_mfma_f32_16x16x32_bf16 v[90:93], v[182:185], v[198:201], v[90:93]
	v_mfma_f32_16x16x32_bf16 v[82:85], v[174:177], v[206:209], v[82:85]
	v_mfma_f32_16x16x32_bf16 v[74:77], v[182:185], v[206:209], v[74:77]
	v_mfma_f32_16x16x32_bf16 v[70:73], v[174:177], v[214:217], v[70:73]
	v_mfma_f32_16x16x32_bf16 v[66:69], v[182:185], v[214:217], v[66:69]
	s_setprio 0
	s_barrier
	s_add_i32 s66, s54, s41
	v_lshl_add_u64 v[146:147], s[34:35], 0, v[132:133]
	s_mov_b32 m0, s66
	ds_read_b128 v[186:189], v152 offset:16384
	ds_read_b128 v[190:193], v152 offset:17408
	ds_read_b128 v[194:197], v152 offset:18432
	ds_read_b128 v[198:201], v152 offset:19456
	ds_read_b128 v[202:205], v152 offset:20480
	ds_read_b128 v[206:209], v152 offset:21504
	ds_read_b128 v[210:213], v152 offset:22528
	ds_read_b128 v[214:217], v152 offset:23552
	global_load_lds_dwordx4 v[146:147], off
	s_add_i32 m0, s66, 0x2000
	s_add_u32 s66, s34, 0x40000
	v_lshl_add_u64 v[218:219], s[34:35], 0, v[136:137]
	s_addc_u32 s67, s35, 0
	s_add_i32 s68, s55, s41
	global_load_lds_dwordx4 v[218:219], off
	v_lshl_add_u64 v[220:221], s[66:67], 0, v[132:133]
	s_mov_b32 m0, s68
	v_lshl_add_u64 v[222:223], s[36:37], 0, v[134:135]
	global_load_lds_dwordx4 v[220:221], off
	v_lshl_add_u64 v[220:221], s[66:67], 0, v[136:137]
	s_add_i32 m0, s68, 0x2000
	s_nop 0
	global_load_lds_dwordx4 v[220:221], off
	v_lshl_add_u64 v[220:221], s[36:37], 0, v[130:131]
	s_mov_b32 m0, s29
	s_nop 0
	global_load_lds_dwordx4 v[220:221], off
	s_mov_b32 m0, s42
	s_nop 0
	global_load_lds_dwordx4 v[222:223], off
	s_waitcnt vmcnt(8)
	s_waitcnt lgkmcnt(0)
	s_barrier
	s_setprio 1
	v_mfma_f32_16x16x32_bf16 v[62:65], v[154:157], v[186:189], v[62:65]
	v_mfma_f32_16x16x32_bf16 v[58:61], v[162:165], v[186:189], v[58:61]
	v_mfma_f32_16x16x32_bf16 v[54:57], v[154:157], v[194:197], v[54:57]
	v_mfma_f32_16x16x32_bf16 v[46:49], v[162:165], v[194:197], v[46:49]
	v_mfma_f32_16x16x32_bf16 v[38:41], v[154:157], v[202:205], v[38:41]
	v_mfma_f32_16x16x32_bf16 v[30:33], v[162:165], v[202:205], v[30:33]
	v_mfma_f32_16x16x32_bf16 v[22:25], v[154:157], v[210:213], v[22:25]
	v_mfma_f32_16x16x32_bf16 v[14:17], v[162:165], v[210:213], v[14:17]
	v_mfma_f32_16x16x32_bf16 v[62:65], v[158:161], v[190:193], v[62:65]
	v_mfma_f32_16x16x32_bf16 v[58:61], v[166:169], v[190:193], v[58:61]
	v_mfma_f32_16x16x32_bf16 v[54:57], v[158:161], v[198:201], v[54:57]
	v_mfma_f32_16x16x32_bf16 v[46:49], v[166:169], v[198:201], v[46:49]
	v_mfma_f32_16x16x32_bf16 v[38:41], v[158:161], v[206:209], v[38:41]
	v_mfma_f32_16x16x32_bf16 v[30:33], v[166:169], v[206:209], v[30:33]
	v_mfma_f32_16x16x32_bf16 v[22:25], v[158:161], v[214:217], v[22:25]
	v_mfma_f32_16x16x32_bf16 v[14:17], v[166:169], v[214:217], v[14:17]
	s_setprio 0
	s_setprio 1
	v_mfma_f32_16x16x32_bf16 v[50:53], v[170:173], v[186:189], v[50:53]
	v_mfma_f32_16x16x32_bf16 v[42:45], v[178:181], v[186:189], v[42:45]
	v_mfma_f32_16x16x32_bf16 v[34:37], v[170:173], v[194:197], v[34:37]
	v_mfma_f32_16x16x32_bf16 v[26:29], v[178:181], v[194:197], v[26:29]
	v_mfma_f32_16x16x32_bf16 v[18:21], v[170:173], v[202:205], v[18:21]
	v_mfma_f32_16x16x32_bf16 v[10:13], v[178:181], v[202:205], v[10:13]
	v_mfma_f32_16x16x32_bf16 v[6:9], v[170:173], v[210:213], v[6:9]
	v_mfma_f32_16x16x32_bf16 v[2:5], v[178:181], v[210:213], v[2:5]
	v_mfma_f32_16x16x32_bf16 v[50:53], v[174:177], v[190:193], v[50:53]
	v_mfma_f32_16x16x32_bf16 v[42:45], v[182:185], v[190:193], v[42:45]
	v_mfma_f32_16x16x32_bf16 v[34:37], v[174:177], v[198:201], v[34:37]
	v_mfma_f32_16x16x32_bf16 v[26:29], v[182:185], v[198:201], v[26:29]
	v_mfma_f32_16x16x32_bf16 v[18:21], v[174:177], v[206:209], v[18:21]
	v_mfma_f32_16x16x32_bf16 v[10:13], v[182:185], v[206:209], v[10:13]
	v_mfma_f32_16x16x32_bf16 v[6:9], v[174:177], v[214:217], v[6:9]
	v_mfma_f32_16x16x32_bf16 v[2:5], v[182:185], v[214:217], v[2:5]
	s_setprio 0
	s_barrier
	s_add_i32 s66, 0, 0x18000
	v_add_u32_e32 v153, s66, v148
	s_add_i32 s67, 0, 0x1c000
	ds_read_b128 v[154:157], v153
	ds_read_b128 v[158:161], v153 offset:1024
	ds_read_b128 v[162:165], v153 offset:2048
	ds_read_b128 v[166:169], v153 offset:3072
	v_add_u32_e32 v153, s67, v148
	ds_read_b128 v[170:173], v153
	ds_read_b128 v[174:177], v153 offset:1024
	ds_read_b128 v[178:181], v153 offset:2048
	ds_read_b128 v[182:185], v153 offset:3072
	s_add_u32 s36, s36, 0x40000
	s_addc_u32 s37, s37, 0
	s_mov_b32 m0, s43
	v_lshl_add_u64 v[224:225], s[36:37], 0, v[130:131]
	ds_read_b128 v[186:189], v152 offset:32768
	ds_read_b128 v[190:193], v152 offset:33792
	ds_read_b128 v[194:197], v152 offset:34816
	ds_read_b128 v[198:201], v152 offset:35840
	ds_read_b128 v[202:205], v152 offset:36864
	ds_read_b128 v[206:209], v152 offset:37888
	ds_read_b128 v[210:213], v152 offset:38912
	ds_read_b128 v[214:217], v152 offset:39936
	global_load_lds_dwordx4 v[224:225], off
	v_lshl_add_u64 v[224:225], s[36:37], 0, v[134:135]
	s_mov_b32 m0, s44
	s_nop 0
	global_load_lds_dwordx4 v[224:225], off
	s_waitcnt vmcnt(8)
	s_waitcnt lgkmcnt(0)
	s_barrier
	s_setprio 1
	v_mfma_f32_16x16x32_bf16 v[126:129], v[154:157], v[186:189], v[126:129]
	v_mfma_f32_16x16x32_bf16 v[122:125], v[162:165], v[186:189], v[122:125]
	v_mfma_f32_16x16x32_bf16 v[118:121], v[154:157], v[194:197], v[118:121]
	v_mfma_f32_16x16x32_bf16 v[110:113], v[162:165], v[194:197], v[110:113]
	v_mfma_f32_16x16x32_bf16 v[102:105], v[154:157], v[202:205], v[102:105]
	v_mfma_f32_16x16x32_bf16 v[94:97], v[162:165], v[202:205], v[94:97]
	v_mfma_f32_16x16x32_bf16 v[86:89], v[154:157], v[210:213], v[86:89]
	v_mfma_f32_16x16x32_bf16 v[78:81], v[162:165], v[210:213], v[78:81]
	v_mfma_f32_16x16x32_bf16 v[126:129], v[158:161], v[190:193], v[126:129]
	v_mfma_f32_16x16x32_bf16 v[122:125], v[166:169], v[190:193], v[122:125]
	v_mfma_f32_16x16x32_bf16 v[118:121], v[158:161], v[198:201], v[118:121]
	v_mfma_f32_16x16x32_bf16 v[110:113], v[166:169], v[198:201], v[110:113]
	v_mfma_f32_16x16x32_bf16 v[102:105], v[158:161], v[206:209], v[102:105]
	v_mfma_f32_16x16x32_bf16 v[94:97], v[166:169], v[206:209], v[94:97]
	v_mfma_f32_16x16x32_bf16 v[86:89], v[158:161], v[214:217], v[86:89]
	v_mfma_f32_16x16x32_bf16 v[78:81], v[166:169], v[214:217], v[78:81]
	s_setprio 0
	s_setprio 1
	v_mfma_f32_16x16x32_bf16 v[114:117], v[170:173], v[186:189], v[114:117]
	v_mfma_f32_16x16x32_bf16 v[106:109], v[178:181], v[186:189], v[106:109]
	v_mfma_f32_16x16x32_bf16 v[98:101], v[170:173], v[194:197], v[98:101]
	v_mfma_f32_16x16x32_bf16 v[90:93], v[178:181], v[194:197], v[90:93]
	v_mfma_f32_16x16x32_bf16 v[82:85], v[170:173], v[202:205], v[82:85]
	v_mfma_f32_16x16x32_bf16 v[74:77], v[178:181], v[202:205], v[74:77]
	v_mfma_f32_16x16x32_bf16 v[70:73], v[170:173], v[210:213], v[70:73]
	v_mfma_f32_16x16x32_bf16 v[66:69], v[178:181], v[210:213], v[66:69]
	v_mfma_f32_16x16x32_bf16 v[114:117], v[174:177], v[190:193], v[114:117]
	v_mfma_f32_16x16x32_bf16 v[106:109], v[182:185], v[190:193], v[106:109]
	v_mfma_f32_16x16x32_bf16 v[98:101], v[174:177], v[198:201], v[98:101]
	v_mfma_f32_16x16x32_bf16 v[90:93], v[182:185], v[198:201], v[90:93]
	v_mfma_f32_16x16x32_bf16 v[82:85], v[174:177], v[206:209], v[82:85]
	v_mfma_f32_16x16x32_bf16 v[74:77], v[182:185], v[206:209], v[74:77]
	v_mfma_f32_16x16x32_bf16 v[70:73], v[174:177], v[214:217], v[70:73]
	v_mfma_f32_16x16x32_bf16 v[66:69], v[182:185], v[214:217], v[66:69]
	s_setprio 0
	s_barrier
	s_add_i32 s36, s66, s41
	v_lshl_add_u64 v[146:147], v[146:147], 0, s[10:11]
	s_mov_b32 m0, s36
	ds_read_b128 v[186:189], v152 offset:49152
	ds_read_b128 v[190:193], v152 offset:50176
	ds_read_b128 v[194:197], v152 offset:51200
	ds_read_b128 v[198:201], v152 offset:52224
	ds_read_b128 v[202:205], v152 offset:53248
	ds_read_b128 v[206:209], v152 offset:54272
	ds_read_b128 v[210:213], v152 offset:55296
	ds_read_b128 v[214:217], v152 offset:56320
	global_load_lds_dwordx4 v[146:147], off
	s_add_i32 m0, s36, 0x2000
	s_add_u32 s34, s34, 0x40080
	v_lshl_add_u64 v[146:147], v[218:219], 0, s[10:11]
	s_addc_u32 s35, s35, 0
	s_add_i32 s36, s67, s41
	global_load_lds_dwordx4 v[146:147], off
	v_lshl_add_u64 v[146:147], s[34:35], 0, v[132:133]
	s_mov_b32 m0, s36
	s_nop 0
	global_load_lds_dwordx4 v[146:147], off
	v_lshl_add_u64 v[146:147], s[34:35], 0, v[136:137]
	s_add_i32 m0, s36, 0x2000
	s_nop 0
	global_load_lds_dwordx4 v[146:147], off
	v_lshl_add_u64 v[146:147], v[220:221], 0, s[10:11]
	s_mov_b32 m0, s46
	s_nop 0
	global_load_lds_dwordx4 v[146:147], off
	v_lshl_add_u64 v[146:147], v[222:223], 0, s[10:11]
	s_mov_b32 m0, s47
	s_nop 0
	global_load_lds_dwordx4 v[146:147], off
	s_waitcnt vmcnt(8)
	s_waitcnt lgkmcnt(0)
	s_barrier
	s_add_i32 s65, s65, 2
	s_add_u32 s30, s30, 0x100
	s_addc_u32 s31, s31, 0
	s_add_u32 s63, s63, 0x100
	s_addc_u32 s64, s64, 0
	s_cmp_gt_u32 s65, 13
	s_setprio 1
	s_waitcnt lgkmcnt(0)
	v_mfma_f32_16x16x32_bf16 v[62:65], v[154:157], v[186:189], v[62:65]
	v_mfma_f32_16x16x32_bf16 v[58:61], v[162:165], v[186:189], v[58:61]
	v_mfma_f32_16x16x32_bf16 v[54:57], v[154:157], v[194:197], v[54:57]
	v_mfma_f32_16x16x32_bf16 v[46:49], v[162:165], v[194:197], v[46:49]
	v_mfma_f32_16x16x32_bf16 v[38:41], v[154:157], v[202:205], v[38:41]
	v_mfma_f32_16x16x32_bf16 v[30:33], v[162:165], v[202:205], v[30:33]
	v_mfma_f32_16x16x32_bf16 v[22:25], v[154:157], v[210:213], v[22:25]
	v_mfma_f32_16x16x32_bf16 v[14:17], v[162:165], v[210:213], v[14:17]
	v_mfma_f32_16x16x32_bf16 v[62:65], v[158:161], v[190:193], v[62:65]
	v_mfma_f32_16x16x32_bf16 v[58:61], v[166:169], v[190:193], v[58:61]
	v_mfma_f32_16x16x32_bf16 v[54:57], v[158:161], v[198:201], v[54:57]
	v_mfma_f32_16x16x32_bf16 v[46:49], v[166:169], v[198:201], v[46:49]
	v_mfma_f32_16x16x32_bf16 v[38:41], v[158:161], v[206:209], v[38:41]
	v_mfma_f32_16x16x32_bf16 v[30:33], v[166:169], v[206:209], v[30:33]
	v_mfma_f32_16x16x32_bf16 v[22:25], v[158:161], v[214:217], v[22:25]
	v_mfma_f32_16x16x32_bf16 v[14:17], v[166:169], v[214:217], v[14:17]
	s_setprio 0
	s_setprio 1
	v_mfma_f32_16x16x32_bf16 v[50:53], v[170:173], v[186:189], v[50:53]
	v_mfma_f32_16x16x32_bf16 v[42:45], v[178:181], v[186:189], v[42:45]
	v_mfma_f32_16x16x32_bf16 v[34:37], v[170:173], v[194:197], v[34:37]
	v_mfma_f32_16x16x32_bf16 v[26:29], v[178:181], v[194:197], v[26:29]
	v_mfma_f32_16x16x32_bf16 v[18:21], v[170:173], v[202:205], v[18:21]
	v_mfma_f32_16x16x32_bf16 v[10:13], v[178:181], v[202:205], v[10:13]
	v_mfma_f32_16x16x32_bf16 v[6:9], v[170:173], v[210:213], v[6:9]
	v_mfma_f32_16x16x32_bf16 v[2:5], v[178:181], v[210:213], v[2:5]
	v_mfma_f32_16x16x32_bf16 v[50:53], v[174:177], v[190:193], v[50:53]
	v_mfma_f32_16x16x32_bf16 v[42:45], v[182:185], v[190:193], v[42:45]
	v_mfma_f32_16x16x32_bf16 v[34:37], v[174:177], v[198:201], v[34:37]
	v_mfma_f32_16x16x32_bf16 v[26:29], v[182:185], v[198:201], v[26:29]
	v_mfma_f32_16x16x32_bf16 v[18:21], v[174:177], v[206:209], v[18:21]
	v_mfma_f32_16x16x32_bf16 v[10:13], v[182:185], v[206:209], v[10:13]
	v_mfma_f32_16x16x32_bf16 v[6:9], v[174:177], v[214:217], v[6:9]
	v_mfma_f32_16x16x32_bf16 v[2:5], v[182:185], v[214:217], v[2:5]
	s_setprio 0
	s_barrier
	s_cbranch_scc0 .LBB0_1031
	s_and_b64 vcc, exec, s[12:13]
	s_cbranch_vccz .LBB0_1034
	s_barrier

.LBB0_1166:
	ds_read_b128 v[154:157], v150
	ds_read_b128 v[158:161], v150 offset:1024
	ds_read_b128 v[162:165], v150 offset:2048
	ds_read_b128 v[166:169], v150 offset:3072
	ds_read_b128 v[170:173], v151
	ds_read_b128 v[174:177], v151 offset:1024
	ds_read_b128 v[178:181], v151 offset:2048
	ds_read_b128 v[182:185], v151 offset:3072
	s_add_u32 s34, s30, 0xfffc0080
	s_addc_u32 s35, s31, -1
	s_cmp_eq_u32 s65, 12
	s_cselect_b32 s37, s23, s35
	s_cselect_b32 s36, s61, s34
	s_cselect_b32 s35, s21, s64
	s_cselect_b32 s34, s62, s63
	v_lshl_add_u64 v[146:147], s[30:31], 0, v[138:139]
	s_add_i32 m0, s29, 0xc000
	ds_read_b128 v[186:189], v152
	ds_read_b128 v[190:193], v152 offset:1024
	ds_read_b128 v[194:197], v152 offset:2048
	ds_read_b128 v[198:201], v152 offset:3072
	ds_read_b128 v[202:205], v152 offset:4096
	ds_read_b128 v[206:209], v152 offset:5120
	ds_read_b128 v[210:213], v152 offset:6144
	ds_read_b128 v[214:217], v152 offset:7168
	global_load_lds_dwordx4 v[146:147], off
	v_lshl_add_u64 v[146:147], s[30:31], 0, v[140:141]
	s_add_i32 m0, s29, 0xe000
	s_nop 0
	global_load_lds_dwordx4 v[146:147], off
	s_waitcnt vmcnt(8)
	s_waitcnt lgkmcnt(0)
	s_barrier
	s_setprio 1
	v_mfma_f32_16x16x32_bf16 v[126:129], v[154:157], v[186:189], v[126:129]
	v_mfma_f32_16x16x32_bf16 v[122:125], v[162:165], v[186:189], v[122:125]
	v_mfma_f32_16x16x32_bf16 v[110:113], v[154:157], v[194:197], v[110:113]
	v_mfma_f32_16x16x32_bf16 v[106:109], v[162:165], v[194:197], v[106:109]
	v_mfma_f32_16x16x32_bf16 v[94:97], v[154:157], v[202:205], v[94:97]
	v_mfma_f32_16x16x32_bf16 v[90:93], v[162:165], v[202:205], v[90:93]
	v_mfma_f32_16x16x32_bf16 v[78:81], v[154:157], v[210:213], v[78:81]
	v_mfma_f32_16x16x32_bf16 v[74:77], v[162:165], v[210:213], v[74:77]
	v_mfma_f32_16x16x32_bf16 v[126:129], v[158:161], v[190:193], v[126:129]
	v_mfma_f32_16x16x32_bf16 v[122:125], v[166:169], v[190:193], v[122:125]
	v_mfma_f32_16x16x32_bf16 v[110:113], v[158:161], v[198:201], v[110:113]
	v_mfma_f32_16x16x32_bf16 v[106:109], v[166:169], v[198:201], v[106:109]
	v_mfma_f32_16x16x32_bf16 v[94:97], v[158:161], v[206:209], v[94:97]
	v_mfma_f32_16x16x32_bf16 v[90:93], v[166:169], v[206:209], v[90:93]
	v_mfma_f32_16x16x32_bf16 v[78:81], v[158:161], v[214:217], v[78:81]
	v_mfma_f32_16x16x32_bf16 v[74:77], v[166:169], v[214:217], v[74:77]
	s_setprio 0
	s_setprio 1
	v_mfma_f32_16x16x32_bf16 v[118:121], v[170:173], v[186:189], v[118:121]
	v_mfma_f32_16x16x32_bf16 v[114:117], v[178:181], v[186:189], v[114:117]
	v_mfma_f32_16x16x32_bf16 v[102:105], v[170:173], v[194:197], v[102:105]
	v_mfma_f32_16x16x32_bf16 v[98:101], v[178:181], v[194:197], v[98:101]
	v_mfma_f32_16x16x32_bf16 v[86:89], v[170:173], v[202:205], v[86:89]
	v_mfma_f32_16x16x32_bf16 v[82:85], v[178:181], v[202:205], v[82:85]
	v_mfma_f32_16x16x32_bf16 v[70:73], v[170:173], v[210:213], v[70:73]
	v_mfma_f32_16x16x32_bf16 v[66:69], v[178:181], v[210:213], v[66:69]
	v_mfma_f32_16x16x32_bf16 v[118:121], v[174:177], v[190:193], v[118:121]
	v_mfma_f32_16x16x32_bf16 v[114:117], v[182:185], v[190:193], v[114:117]
	v_mfma_f32_16x16x32_bf16 v[102:105], v[174:177], v[198:201], v[102:105]
	v_mfma_f32_16x16x32_bf16 v[98:101], v[182:185], v[198:201], v[98:101]
	v_mfma_f32_16x16x32_bf16 v[86:89], v[174:177], v[206:209], v[86:89]
	v_mfma_f32_16x16x32_bf16 v[82:85], v[182:185], v[206:209], v[82:85]
	v_mfma_f32_16x16x32_bf16 v[70:73], v[174:177], v[214:217], v[70:73]
	v_mfma_f32_16x16x32_bf16 v[66:69], v[182:185], v[214:217], v[66:69]
	s_setprio 0
	s_barrier
	s_add_i32 s66, s54, s41
	v_lshl_add_u64 v[146:147], s[34:35], 0, v[132:133]
	s_mov_b32 m0, s66
	ds_read_b128 v[186:189], v152 offset:16384
	ds_read_b128 v[190:193], v152 offset:17408
	ds_read_b128 v[194:197], v152 offset:18432
	ds_read_b128 v[198:201], v152 offset:19456
	ds_read_b128 v[202:205], v152 offset:20480
	ds_read_b128 v[206:209], v152 offset:21504
	ds_read_b128 v[210:213], v152 offset:22528
	ds_read_b128 v[214:217], v152 offset:23552
	global_load_lds_dwordx4 v[146:147], off
	s_add_i32 m0, s66, 0x2000
	s_add_u32 s66, s34, 0x40000
	v_lshl_add_u64 v[218:219], s[34:35], 0, v[136:137]
	s_addc_u32 s67, s35, 0
	s_add_i32 s68, s55, s41
	global_load_lds_dwordx4 v[218:219], off
	v_lshl_add_u64 v[220:221], s[66:67], 0, v[132:133]
	s_mov_b32 m0, s68
	v_lshl_add_u64 v[222:223], s[36:37], 0, v[134:135]
	global_load_lds_dwordx4 v[220:221], off
	v_lshl_add_u64 v[220:221], s[66:67], 0, v[136:137]
	s_add_i32 m0, s68, 0x2000
	s_nop 0
	global_load_lds_dwordx4 v[220:221], off
	v_lshl_add_u64 v[220:221], s[36:37], 0, v[130:131]
	s_mov_b32 m0, s29
	s_nop 0
	global_load_lds_dwordx4 v[220:221], off
	s_mov_b32 m0, s42
	s_nop 0
	global_load_lds_dwordx4 v[222:223], off
	s_waitcnt vmcnt(8)
	s_waitcnt lgkmcnt(0)
	s_barrier
	s_setprio 1
	v_mfma_f32_16x16x32_bf16 v[62:65], v[154:157], v[186:189], v[62:65]
	v_mfma_f32_16x16x32_bf16 v[58:61], v[162:165], v[186:189], v[58:61]
	v_mfma_f32_16x16x32_bf16 v[46:49], v[154:157], v[194:197], v[46:49]
	v_mfma_f32_16x16x32_bf16 v[42:45], v[162:165], v[194:197], v[42:45]
	v_mfma_f32_16x16x32_bf16 v[30:33], v[154:157], v[202:205], v[30:33]
	v_mfma_f32_16x16x32_bf16 v[26:29], v[162:165], v[202:205], v[26:29]
	v_mfma_f32_16x16x32_bf16 v[14:17], v[154:157], v[210:213], v[14:17]
	v_mfma_f32_16x16x32_bf16 v[10:13], v[162:165], v[210:213], v[10:13]
	v_mfma_f32_16x16x32_bf16 v[62:65], v[158:161], v[190:193], v[62:65]
	v_mfma_f32_16x16x32_bf16 v[58:61], v[166:169], v[190:193], v[58:61]
	v_mfma_f32_16x16x32_bf16 v[46:49], v[158:161], v[198:201], v[46:49]
	v_mfma_f32_16x16x32_bf16 v[42:45], v[166:169], v[198:201], v[42:45]
	v_mfma_f32_16x16x32_bf16 v[30:33], v[158:161], v[206:209], v[30:33]
	v_mfma_f32_16x16x32_bf16 v[26:29], v[166:169], v[206:209], v[26:29]
	v_mfma_f32_16x16x32_bf16 v[14:17], v[158:161], v[214:217], v[14:17]
	v_mfma_f32_16x16x32_bf16 v[10:13], v[166:169], v[214:217], v[10:13]
	s_setprio 0
	s_setprio 1
	v_mfma_f32_16x16x32_bf16 v[54:57], v[170:173], v[186:189], v[54:57]
	v_mfma_f32_16x16x32_bf16 v[50:53], v[178:181], v[186:189], v[50:53]
	v_mfma_f32_16x16x32_bf16 v[38:41], v[170:173], v[194:197], v[38:41]
	v_mfma_f32_16x16x32_bf16 v[34:37], v[178:181], v[194:197], v[34:37]
	v_mfma_f32_16x16x32_bf16 v[22:25], v[170:173], v[202:205], v[22:25]
	v_mfma_f32_16x16x32_bf16 v[18:21], v[178:181], v[202:205], v[18:21]
	v_mfma_f32_16x16x32_bf16 v[6:9], v[170:173], v[210:213], v[6:9]
	v_mfma_f32_16x16x32_bf16 v[2:5], v[178:181], v[210:213], v[2:5]
	v_mfma_f32_16x16x32_bf16 v[54:57], v[174:177], v[190:193], v[54:57]
	v_mfma_f32_16x16x32_bf16 v[50:53], v[182:185], v[190:193], v[50:53]
	v_mfma_f32_16x16x32_bf16 v[38:41], v[174:177], v[198:201], v[38:41]
	v_mfma_f32_16x16x32_bf16 v[34:37], v[182:185], v[198:201], v[34:37]
	v_mfma_f32_16x16x32_bf16 v[22:25], v[174:177], v[206:209], v[22:25]
	v_mfma_f32_16x16x32_bf16 v[18:21], v[182:185], v[206:209], v[18:21]
	v_mfma_f32_16x16x32_bf16 v[6:9], v[174:177], v[214:217], v[6:9]
	v_mfma_f32_16x16x32_bf16 v[2:5], v[182:185], v[214:217], v[2:5]
	s_setprio 0
	s_barrier
	s_add_i32 s66, 0, 0x18000
	v_add_u32_e32 v153, s66, v148
	s_add_i32 s67, 0, 0x1c000
	ds_read_b128 v[154:157], v153
	ds_read_b128 v[158:161], v153 offset:1024
	ds_read_b128 v[162:165], v153 offset:2048
	ds_read_b128 v[166:169], v153 offset:3072
	v_add_u32_e32 v153, s67, v148
	ds_read_b128 v[170:173], v153
	ds_read_b128 v[174:177], v153 offset:1024
	ds_read_b128 v[178:181], v153 offset:2048
	ds_read_b128 v[182:185], v153 offset:3072
	s_add_u32 s36, s36, 0x40000
	s_addc_u32 s37, s37, 0
	s_mov_b32 m0, s43
	v_lshl_add_u64 v[224:225], s[36:37], 0, v[130:131]
	ds_read_b128 v[186:189], v152 offset:32768
	ds_read_b128 v[190:193], v152 offset:33792
	ds_read_b128 v[194:197], v152 offset:34816
	ds_read_b128 v[198:201], v152 offset:35840
	ds_read_b128 v[202:205], v152 offset:36864
	ds_read_b128 v[206:209], v152 offset:37888
	ds_read_b128 v[210:213], v152 offset:38912
	ds_read_b128 v[214:217], v152 offset:39936
	global_load_lds_dwordx4 v[224:225], off
	v_lshl_add_u64 v[224:225], s[36:37], 0, v[134:135]
	s_mov_b32 m0, s44
	s_nop 0
	global_load_lds_dwordx4 v[224:225], off
	s_waitcnt vmcnt(8)
	s_waitcnt lgkmcnt(0)
	s_barrier
	s_setprio 1
	v_mfma_f32_16x16x32_bf16 v[126:129], v[154:157], v[186:189], v[126:129]
	v_mfma_f32_16x16x32_bf16 v[122:125], v[162:165], v[186:189], v[122:125]
	v_mfma_f32_16x16x32_bf16 v[110:113], v[154:157], v[194:197], v[110:113]
	v_mfma_f32_16x16x32_bf16 v[106:109], v[162:165], v[194:197], v[106:109]
	v_mfma_f32_16x16x32_bf16 v[94:97], v[154:157], v[202:205], v[94:97]
	v_mfma_f32_16x16x32_bf16 v[90:93], v[162:165], v[202:205], v[90:93]
	v_mfma_f32_16x16x32_bf16 v[78:81], v[154:157], v[210:213], v[78:81]
	v_mfma_f32_16x16x32_bf16 v[74:77], v[162:165], v[210:213], v[74:77]
	v_mfma_f32_16x16x32_bf16 v[126:129], v[158:161], v[190:193], v[126:129]
	v_mfma_f32_16x16x32_bf16 v[122:125], v[166:169], v[190:193], v[122:125]
	v_mfma_f32_16x16x32_bf16 v[110:113], v[158:161], v[198:201], v[110:113]
	v_mfma_f32_16x16x32_bf16 v[106:109], v[166:169], v[198:201], v[106:109]
	v_mfma_f32_16x16x32_bf16 v[94:97], v[158:161], v[206:209], v[94:97]
	v_mfma_f32_16x16x32_bf16 v[90:93], v[166:169], v[206:209], v[90:93]
	v_mfma_f32_16x16x32_bf16 v[78:81], v[158:161], v[214:217], v[78:81]
	v_mfma_f32_16x16x32_bf16 v[74:77], v[166:169], v[214:217], v[74:77]
	s_setprio 0
	s_setprio 1
	v_mfma_f32_16x16x32_bf16 v[118:121], v[170:173], v[186:189], v[118:121]
	v_mfma_f32_16x16x32_bf16 v[114:117], v[178:181], v[186:189], v[114:117]
	v_mfma_f32_16x16x32_bf16 v[102:105], v[170:173], v[194:197], v[102:105]
	v_mfma_f32_16x16x32_bf16 v[98:101], v[178:181], v[194:197], v[98:101]
	v_mfma_f32_16x16x32_bf16 v[86:89], v[170:173], v[202:205], v[86:89]
	v_mfma_f32_16x16x32_bf16 v[82:85], v[178:181], v[202:205], v[82:85]
	v_mfma_f32_16x16x32_bf16 v[70:73], v[170:173], v[210:213], v[70:73]
	v_mfma_f32_16x16x32_bf16 v[66:69], v[178:181], v[210:213], v[66:69]
	v_mfma_f32_16x16x32_bf16 v[118:121], v[174:177], v[190:193], v[118:121]
	v_mfma_f32_16x16x32_bf16 v[114:117], v[182:185], v[190:193], v[114:117]
	v_mfma_f32_16x16x32_bf16 v[102:105], v[174:177], v[198:201], v[102:105]
	v_mfma_f32_16x16x32_bf16 v[98:101], v[182:185], v[198:201], v[98:101]
	v_mfma_f32_16x16x32_bf16 v[86:89], v[174:177], v[206:209], v[86:89]
	v_mfma_f32_16x16x32_bf16 v[82:85], v[182:185], v[206:209], v[82:85]
	v_mfma_f32_16x16x32_bf16 v[70:73], v[174:177], v[214:217], v[70:73]
	v_mfma_f32_16x16x32_bf16 v[66:69], v[182:185], v[214:217], v[66:69]
	s_setprio 0
	s_barrier
	s_add_i32 s36, s66, s41
	v_lshl_add_u64 v[146:147], v[146:147], 0, s[8:9]
	s_mov_b32 m0, s36
	ds_read_b128 v[186:189], v152 offset:49152
	ds_read_b128 v[190:193], v152 offset:50176
	ds_read_b128 v[194:197], v152 offset:51200
	ds_read_b128 v[198:201], v152 offset:52224
	ds_read_b128 v[202:205], v152 offset:53248
	ds_read_b128 v[206:209], v152 offset:54272
	ds_read_b128 v[210:213], v152 offset:55296
	ds_read_b128 v[214:217], v152 offset:56320
	global_load_lds_dwordx4 v[146:147], off
	s_add_i32 m0, s36, 0x2000
	s_add_u32 s34, s34, 0x40080
	v_lshl_add_u64 v[146:147], v[218:219], 0, s[8:9]
	s_addc_u32 s35, s35, 0
	s_add_i32 s36, s67, s41
	global_load_lds_dwordx4 v[146:147], off
	v_lshl_add_u64 v[146:147], s[34:35], 0, v[132:133]
	s_mov_b32 m0, s36
	s_nop 0
	global_load_lds_dwordx4 v[146:147], off
	v_lshl_add_u64 v[146:147], s[34:35], 0, v[136:137]
	s_add_i32 m0, s36, 0x2000
	s_nop 0
	global_load_lds_dwordx4 v[146:147], off
	v_lshl_add_u64 v[146:147], v[220:221], 0, s[8:9]
	s_mov_b32 m0, s46
	s_nop 0
	global_load_lds_dwordx4 v[146:147], off
	v_lshl_add_u64 v[146:147], v[222:223], 0, s[8:9]
	s_mov_b32 m0, s47
	s_nop 0
	global_load_lds_dwordx4 v[146:147], off
	s_waitcnt vmcnt(8)
	s_waitcnt lgkmcnt(0)
	s_barrier
	s_add_i32 s65, s65, 2
	s_add_u32 s30, s30, 0x100
	s_addc_u32 s31, s31, 0
	s_add_u32 s63, s63, 0x100
	s_addc_u32 s64, s64, 0
	s_cmp_gt_u32 s65, 13
	s_setprio 1
	s_waitcnt lgkmcnt(0)
	v_mfma_f32_16x16x32_bf16 v[62:65], v[154:157], v[186:189], v[62:65]
	v_mfma_f32_16x16x32_bf16 v[58:61], v[162:165], v[186:189], v[58:61]
	v_mfma_f32_16x16x32_bf16 v[46:49], v[154:157], v[194:197], v[46:49]
	v_mfma_f32_16x16x32_bf16 v[42:45], v[162:165], v[194:197], v[42:45]
	v_mfma_f32_16x16x32_bf16 v[30:33], v[154:157], v[202:205], v[30:33]
	v_mfma_f32_16x16x32_bf16 v[26:29], v[162:165], v[202:205], v[26:29]
	v_mfma_f32_16x16x32_bf16 v[14:17], v[154:157], v[210:213], v[14:17]
	v_mfma_f32_16x16x32_bf16 v[10:13], v[162:165], v[210:213], v[10:13]
	v_mfma_f32_16x16x32_bf16 v[62:65], v[158:161], v[190:193], v[62:65]
	v_mfma_f32_16x16x32_bf16 v[58:61], v[166:169], v[190:193], v[58:61]
	v_mfma_f32_16x16x32_bf16 v[46:49], v[158:161], v[198:201], v[46:49]
	v_mfma_f32_16x16x32_bf16 v[42:45], v[166:169], v[198:201], v[42:45]
	v_mfma_f32_16x16x32_bf16 v[30:33], v[158:161], v[206:209], v[30:33]
	v_mfma_f32_16x16x32_bf16 v[26:29], v[166:169], v[206:209], v[26:29]
	v_mfma_f32_16x16x32_bf16 v[14:17], v[158:161], v[214:217], v[14:17]
	v_mfma_f32_16x16x32_bf16 v[10:13], v[166:169], v[214:217], v[10:13]
	s_setprio 0
	s_setprio 1
	v_mfma_f32_16x16x32_bf16 v[54:57], v[170:173], v[186:189], v[54:57]
	v_mfma_f32_16x16x32_bf16 v[50:53], v[178:181], v[186:189], v[50:53]
	v_mfma_f32_16x16x32_bf16 v[38:41], v[170:173], v[194:197], v[38:41]
	v_mfma_f32_16x16x32_bf16 v[34:37], v[178:181], v[194:197], v[34:37]
	v_mfma_f32_16x16x32_bf16 v[22:25], v[170:173], v[202:205], v[22:25]
	v_mfma_f32_16x16x32_bf16 v[18:21], v[178:181], v[202:205], v[18:21]
	v_mfma_f32_16x16x32_bf16 v[6:9], v[170:173], v[210:213], v[6:9]
	v_mfma_f32_16x16x32_bf16 v[2:5], v[178:181], v[210:213], v[2:5]
	v_mfma_f32_16x16x32_bf16 v[54:57], v[174:177], v[190:193], v[54:57]
	v_mfma_f32_16x16x32_bf16 v[50:53], v[182:185], v[190:193], v[50:53]
	v_mfma_f32_16x16x32_bf16 v[38:41], v[174:177], v[198:201], v[38:41]
	v_mfma_f32_16x16x32_bf16 v[34:37], v[182:185], v[198:201], v[34:37]
	v_mfma_f32_16x16x32_bf16 v[22:25], v[174:177], v[206:209], v[22:25]
	v_mfma_f32_16x16x32_bf16 v[18:21], v[182:185], v[206:209], v[18:21]
	v_mfma_f32_16x16x32_bf16 v[6:9], v[174:177], v[214:217], v[6:9]
	v_mfma_f32_16x16x32_bf16 v[2:5], v[182:185], v[214:217], v[2:5]
	s_setprio 0
	s_barrier
	s_cbranch_scc0 .LBB0_1166
	s_and_b64 vcc, exec, s[10:11]
	s_cbranch_vccz .LBB0_1169
	s_barrier

.LBB0_1241:
	ds_read_b128 v[154:157], v150
	ds_read_b128 v[158:161], v150 offset:1024
	ds_read_b128 v[162:165], v150 offset:2048
	ds_read_b128 v[166:169], v150 offset:3072
	ds_read_b128 v[170:173], v151
	ds_read_b128 v[174:177], v151 offset:1024
	ds_read_b128 v[178:181], v151 offset:2048
	ds_read_b128 v[182:185], v151 offset:3072
	s_add_u32 s34, s30, 0xfff00080
	s_addc_u32 s35, s31, -1
	s_cmp_eq_u32 s65, 60
	s_cselect_b32 s37, s23, s35
	s_cselect_b32 s36, s61, s34
	s_cselect_b32 s35, s21, s64
	s_cselect_b32 s34, s62, s63
	v_lshl_add_u64 v[146:147], s[30:31], 0, v[138:139]
	s_add_i32 m0, s29, 0xc000
	ds_read_b128 v[186:189], v152
	ds_read_b128 v[190:193], v152 offset:1024
	ds_read_b128 v[194:197], v152 offset:2048
	ds_read_b128 v[198:201], v152 offset:3072
	ds_read_b128 v[202:205], v152 offset:4096
	ds_read_b128 v[206:209], v152 offset:5120
	ds_read_b128 v[210:213], v152 offset:6144
	ds_read_b128 v[214:217], v152 offset:7168
	global_load_lds_dwordx4 v[146:147], off
	v_lshl_add_u64 v[146:147], s[30:31], 0, v[140:141]
	s_add_i32 m0, s29, 0xe000
	s_nop 0
	global_load_lds_dwordx4 v[146:147], off
	s_waitcnt vmcnt(8)
	s_waitcnt lgkmcnt(0)
	s_barrier
	s_setprio 1
	v_mfma_f32_16x16x32_bf16 v[126:129], v[154:157], v[186:189], v[126:129]
	v_mfma_f32_16x16x32_bf16 v[122:125], v[162:165], v[186:189], v[122:125]
	v_mfma_f32_16x16x32_bf16 v[118:121], v[154:157], v[194:197], v[118:121]
	v_mfma_f32_16x16x32_bf16 v[110:113], v[162:165], v[194:197], v[110:113]
	v_mfma_f32_16x16x32_bf16 v[102:105], v[154:157], v[202:205], v[102:105]
	v_mfma_f32_16x16x32_bf16 v[94:97], v[162:165], v[202:205], v[94:97]
	v_mfma_f32_16x16x32_bf16 v[86:89], v[154:157], v[210:213], v[86:89]
	v_mfma_f32_16x16x32_bf16 v[78:81], v[162:165], v[210:213], v[78:81]
	v_mfma_f32_16x16x32_bf16 v[126:129], v[158:161], v[190:193], v[126:129]
	v_mfma_f32_16x16x32_bf16 v[122:125], v[166:169], v[190:193], v[122:125]
	v_mfma_f32_16x16x32_bf16 v[118:121], v[158:161], v[198:201], v[118:121]
	v_mfma_f32_16x16x32_bf16 v[110:113], v[166:169], v[198:201], v[110:113]
	v_mfma_f32_16x16x32_bf16 v[102:105], v[158:161], v[206:209], v[102:105]
	v_mfma_f32_16x16x32_bf16 v[94:97], v[166:169], v[206:209], v[94:97]
	v_mfma_f32_16x16x32_bf16 v[86:89], v[158:161], v[214:217], v[86:89]
	v_mfma_f32_16x16x32_bf16 v[78:81], v[166:169], v[214:217], v[78:81]
	s_setprio 0
	s_setprio 1
	v_mfma_f32_16x16x32_bf16 v[114:117], v[170:173], v[186:189], v[114:117]
	v_mfma_f32_16x16x32_bf16 v[106:109], v[178:181], v[186:189], v[106:109]
	v_mfma_f32_16x16x32_bf16 v[98:101], v[170:173], v[194:197], v[98:101]
	v_mfma_f32_16x16x32_bf16 v[90:93], v[178:181], v[194:197], v[90:93]
	v_mfma_f32_16x16x32_bf16 v[82:85], v[170:173], v[202:205], v[82:85]
	v_mfma_f32_16x16x32_bf16 v[74:77], v[178:181], v[202:205], v[74:77]
	v_mfma_f32_16x16x32_bf16 v[70:73], v[170:173], v[210:213], v[70:73]
	v_mfma_f32_16x16x32_bf16 v[66:69], v[178:181], v[210:213], v[66:69]
	v_mfma_f32_16x16x32_bf16 v[114:117], v[174:177], v[190:193], v[114:117]
	v_mfma_f32_16x16x32_bf16 v[106:109], v[182:185], v[190:193], v[106:109]
	v_mfma_f32_16x16x32_bf16 v[98:101], v[174:177], v[198:201], v[98:101]
	v_mfma_f32_16x16x32_bf16 v[90:93], v[182:185], v[198:201], v[90:93]
	v_mfma_f32_16x16x32_bf16 v[82:85], v[174:177], v[206:209], v[82:85]
	v_mfma_f32_16x16x32_bf16 v[74:77], v[182:185], v[206:209], v[74:77]
	v_mfma_f32_16x16x32_bf16 v[70:73], v[174:177], v[214:217], v[70:73]
	v_mfma_f32_16x16x32_bf16 v[66:69], v[182:185], v[214:217], v[66:69]
	s_setprio 0
	s_barrier
	s_add_i32 s66, s54, s41
	v_lshl_add_u64 v[146:147], s[34:35], 0, v[132:133]
	s_mov_b32 m0, s66
	ds_read_b128 v[186:189], v152 offset:16384
	ds_read_b128 v[190:193], v152 offset:17408
	ds_read_b128 v[194:197], v152 offset:18432
	ds_read_b128 v[198:201], v152 offset:19456
	ds_read_b128 v[202:205], v152 offset:20480
	ds_read_b128 v[206:209], v152 offset:21504
	ds_read_b128 v[210:213], v152 offset:22528
	ds_read_b128 v[214:217], v152 offset:23552
	global_load_lds_dwordx4 v[146:147], off
	s_add_i32 m0, s66, 0x2000
	s_add_u32 s66, s34, 0x100000
	v_lshl_add_u64 v[218:219], s[34:35], 0, v[136:137]
	s_addc_u32 s67, s35, 0
	s_add_i32 s68, s55, s41
	global_load_lds_dwordx4 v[218:219], off
	v_lshl_add_u64 v[220:221], s[66:67], 0, v[132:133]
	s_mov_b32 m0, s68
	v_lshl_add_u64 v[222:223], s[36:37], 0, v[134:135]
	global_load_lds_dwordx4 v[220:221], off
	v_lshl_add_u64 v[220:221], s[66:67], 0, v[136:137]
	s_add_i32 m0, s68, 0x2000
	s_nop 0
	global_load_lds_dwordx4 v[220:221], off
	v_lshl_add_u64 v[220:221], s[36:37], 0, v[130:131]
	s_mov_b32 m0, s29
	s_nop 0
	global_load_lds_dwordx4 v[220:221], off
	s_mov_b32 m0, s42
	s_nop 0
	global_load_lds_dwordx4 v[222:223], off
	s_waitcnt vmcnt(8)
	s_waitcnt lgkmcnt(0)
	s_barrier
	s_setprio 1
	v_mfma_f32_16x16x32_bf16 v[62:65], v[154:157], v[186:189], v[62:65]
	v_mfma_f32_16x16x32_bf16 v[58:61], v[162:165], v[186:189], v[58:61]
	v_mfma_f32_16x16x32_bf16 v[54:57], v[154:157], v[194:197], v[54:57]
	v_mfma_f32_16x16x32_bf16 v[46:49], v[162:165], v[194:197], v[46:49]
	v_mfma_f32_16x16x32_bf16 v[38:41], v[154:157], v[202:205], v[38:41]
	v_mfma_f32_16x16x32_bf16 v[30:33], v[162:165], v[202:205], v[30:33]
	v_mfma_f32_16x16x32_bf16 v[22:25], v[154:157], v[210:213], v[22:25]
	v_mfma_f32_16x16x32_bf16 v[14:17], v[162:165], v[210:213], v[14:17]
	v_mfma_f32_16x16x32_bf16 v[62:65], v[158:161], v[190:193], v[62:65]
	v_mfma_f32_16x16x32_bf16 v[58:61], v[166:169], v[190:193], v[58:61]
	v_mfma_f32_16x16x32_bf16 v[54:57], v[158:161], v[198:201], v[54:57]
	v_mfma_f32_16x16x32_bf16 v[46:49], v[166:169], v[198:201], v[46:49]
	v_mfma_f32_16x16x32_bf16 v[38:41], v[158:161], v[206:209], v[38:41]
	v_mfma_f32_16x16x32_bf16 v[30:33], v[166:169], v[206:209], v[30:33]
	v_mfma_f32_16x16x32_bf16 v[22:25], v[158:161], v[214:217], v[22:25]
	v_mfma_f32_16x16x32_bf16 v[14:17], v[166:169], v[214:217], v[14:17]
	s_setprio 0
	s_setprio 1
	v_mfma_f32_16x16x32_bf16 v[50:53], v[170:173], v[186:189], v[50:53]
	v_mfma_f32_16x16x32_bf16 v[42:45], v[178:181], v[186:189], v[42:45]
	v_mfma_f32_16x16x32_bf16 v[34:37], v[170:173], v[194:197], v[34:37]
	v_mfma_f32_16x16x32_bf16 v[26:29], v[178:181], v[194:197], v[26:29]
	v_mfma_f32_16x16x32_bf16 v[18:21], v[170:173], v[202:205], v[18:21]
	v_mfma_f32_16x16x32_bf16 v[10:13], v[178:181], v[202:205], v[10:13]
	v_mfma_f32_16x16x32_bf16 v[6:9], v[170:173], v[210:213], v[6:9]
	v_mfma_f32_16x16x32_bf16 v[2:5], v[178:181], v[210:213], v[2:5]
	v_mfma_f32_16x16x32_bf16 v[50:53], v[174:177], v[190:193], v[50:53]
	v_mfma_f32_16x16x32_bf16 v[42:45], v[182:185], v[190:193], v[42:45]
	v_mfma_f32_16x16x32_bf16 v[34:37], v[174:177], v[198:201], v[34:37]
	v_mfma_f32_16x16x32_bf16 v[26:29], v[182:185], v[198:201], v[26:29]
	v_mfma_f32_16x16x32_bf16 v[18:21], v[174:177], v[206:209], v[18:21]
	v_mfma_f32_16x16x32_bf16 v[10:13], v[182:185], v[206:209], v[10:13]
	v_mfma_f32_16x16x32_bf16 v[6:9], v[174:177], v[214:217], v[6:9]
	v_mfma_f32_16x16x32_bf16 v[2:5], v[182:185], v[214:217], v[2:5]
	s_setprio 0
	s_barrier
	s_add_i32 s66, 0, 0x18000
	v_add_u32_e32 v153, s66, v148
	s_add_i32 s67, 0, 0x1c000
	ds_read_b128 v[154:157], v153
	ds_read_b128 v[158:161], v153 offset:1024
	ds_read_b128 v[162:165], v153 offset:2048
	ds_read_b128 v[166:169], v153 offset:3072
	v_add_u32_e32 v153, s67, v148
	ds_read_b128 v[170:173], v153
	ds_read_b128 v[174:177], v153 offset:1024
	ds_read_b128 v[178:181], v153 offset:2048
	ds_read_b128 v[182:185], v153 offset:3072
	s_add_u32 s36, s36, 0x100000
	s_addc_u32 s37, s37, 0
	s_mov_b32 m0, s43
	v_lshl_add_u64 v[224:225], s[36:37], 0, v[130:131]
	ds_read_b128 v[186:189], v152 offset:32768
	ds_read_b128 v[190:193], v152 offset:33792
	ds_read_b128 v[194:197], v152 offset:34816
	ds_read_b128 v[198:201], v152 offset:35840
	ds_read_b128 v[202:205], v152 offset:36864
	ds_read_b128 v[206:209], v152 offset:37888
	ds_read_b128 v[210:213], v152 offset:38912
	ds_read_b128 v[214:217], v152 offset:39936
	global_load_lds_dwordx4 v[224:225], off
	v_lshl_add_u64 v[224:225], s[36:37], 0, v[134:135]
	s_mov_b32 m0, s44
	s_nop 0
	global_load_lds_dwordx4 v[224:225], off
	s_waitcnt vmcnt(8)
	s_waitcnt lgkmcnt(0)
	s_barrier
	s_setprio 1
	v_mfma_f32_16x16x32_bf16 v[126:129], v[154:157], v[186:189], v[126:129]
	v_mfma_f32_16x16x32_bf16 v[122:125], v[162:165], v[186:189], v[122:125]
	v_mfma_f32_16x16x32_bf16 v[118:121], v[154:157], v[194:197], v[118:121]
	v_mfma_f32_16x16x32_bf16 v[110:113], v[162:165], v[194:197], v[110:113]
	v_mfma_f32_16x16x32_bf16 v[102:105], v[154:157], v[202:205], v[102:105]
	v_mfma_f32_16x16x32_bf16 v[94:97], v[162:165], v[202:205], v[94:97]
	v_mfma_f32_16x16x32_bf16 v[86:89], v[154:157], v[210:213], v[86:89]
	v_mfma_f32_16x16x32_bf16 v[78:81], v[162:165], v[210:213], v[78:81]
	v_mfma_f32_16x16x32_bf16 v[126:129], v[158:161], v[190:193], v[126:129]
	v_mfma_f32_16x16x32_bf16 v[122:125], v[166:169], v[190:193], v[122:125]
	v_mfma_f32_16x16x32_bf16 v[118:121], v[158:161], v[198:201], v[118:121]
	v_mfma_f32_16x16x32_bf16 v[110:113], v[166:169], v[198:201], v[110:113]
	v_mfma_f32_16x16x32_bf16 v[102:105], v[158:161], v[206:209], v[102:105]
	v_mfma_f32_16x16x32_bf16 v[94:97], v[166:169], v[206:209], v[94:97]
	v_mfma_f32_16x16x32_bf16 v[86:89], v[158:161], v[214:217], v[86:89]
	v_mfma_f32_16x16x32_bf16 v[78:81], v[166:169], v[214:217], v[78:81]
	s_setprio 0
	s_setprio 1
	v_mfma_f32_16x16x32_bf16 v[114:117], v[170:173], v[186:189], v[114:117]
	v_mfma_f32_16x16x32_bf16 v[106:109], v[178:181], v[186:189], v[106:109]
	v_mfma_f32_16x16x32_bf16 v[98:101], v[170:173], v[194:197], v[98:101]
	v_mfma_f32_16x16x32_bf16 v[90:93], v[178:181], v[194:197], v[90:93]
	v_mfma_f32_16x16x32_bf16 v[82:85], v[170:173], v[202:205], v[82:85]
	v_mfma_f32_16x16x32_bf16 v[74:77], v[178:181], v[202:205], v[74:77]
	v_mfma_f32_16x16x32_bf16 v[70:73], v[170:173], v[210:213], v[70:73]
	v_mfma_f32_16x16x32_bf16 v[66:69], v[178:181], v[210:213], v[66:69]
	v_mfma_f32_16x16x32_bf16 v[114:117], v[174:177], v[190:193], v[114:117]
	v_mfma_f32_16x16x32_bf16 v[106:109], v[182:185], v[190:193], v[106:109]
	v_mfma_f32_16x16x32_bf16 v[98:101], v[174:177], v[198:201], v[98:101]
	v_mfma_f32_16x16x32_bf16 v[90:93], v[182:185], v[198:201], v[90:93]
	v_mfma_f32_16x16x32_bf16 v[82:85], v[174:177], v[206:209], v[82:85]
	v_mfma_f32_16x16x32_bf16 v[74:77], v[182:185], v[206:209], v[74:77]
	v_mfma_f32_16x16x32_bf16 v[70:73], v[174:177], v[214:217], v[70:73]
	v_mfma_f32_16x16x32_bf16 v[66:69], v[182:185], v[214:217], v[66:69]
	s_setprio 0
	s_barrier
	s_add_i32 s36, s66, s41
	v_lshl_add_u64 v[146:147], v[146:147], 0, s[8:9]
	s_mov_b32 m0, s36
	ds_read_b128 v[186:189], v152 offset:49152
	ds_read_b128 v[190:193], v152 offset:50176
	ds_read_b128 v[194:197], v152 offset:51200
	ds_read_b128 v[198:201], v152 offset:52224
	ds_read_b128 v[202:205], v152 offset:53248
	ds_read_b128 v[206:209], v152 offset:54272
	ds_read_b128 v[210:213], v152 offset:55296
	ds_read_b128 v[214:217], v152 offset:56320
	global_load_lds_dwordx4 v[146:147], off
	s_add_i32 m0, s36, 0x2000
	s_add_u32 s34, s34, 0x100080
	v_lshl_add_u64 v[146:147], v[218:219], 0, s[8:9]
	s_addc_u32 s35, s35, 0
	s_add_i32 s36, s67, s41
	global_load_lds_dwordx4 v[146:147], off
	v_lshl_add_u64 v[146:147], s[34:35], 0, v[132:133]
	s_mov_b32 m0, s36
	s_nop 0
	global_load_lds_dwordx4 v[146:147], off
	v_lshl_add_u64 v[146:147], s[34:35], 0, v[136:137]
	s_add_i32 m0, s36, 0x2000
	s_nop 0
	global_load_lds_dwordx4 v[146:147], off
	v_lshl_add_u64 v[146:147], v[220:221], 0, s[8:9]
	s_mov_b32 m0, s46
	s_nop 0
	global_load_lds_dwordx4 v[146:147], off
	v_lshl_add_u64 v[146:147], v[222:223], 0, s[8:9]
	s_mov_b32 m0, s47
	s_nop 0
	global_load_lds_dwordx4 v[146:147], off
	s_waitcnt vmcnt(8)
	s_waitcnt lgkmcnt(0)
	s_barrier
	s_add_i32 s65, s65, 2
	s_add_u32 s30, s30, 0x100
	s_addc_u32 s31, s31, 0
	s_add_u32 s63, s63, 0x100
	s_addc_u32 s64, s64, 0
	s_cmp_gt_u32 s65, 61
	s_setprio 1
	s_waitcnt lgkmcnt(0)
	v_mfma_f32_16x16x32_bf16 v[62:65], v[154:157], v[186:189], v[62:65]
	v_mfma_f32_16x16x32_bf16 v[58:61], v[162:165], v[186:189], v[58:61]
	v_mfma_f32_16x16x32_bf16 v[54:57], v[154:157], v[194:197], v[54:57]
	v_mfma_f32_16x16x32_bf16 v[46:49], v[162:165], v[194:197], v[46:49]
	v_mfma_f32_16x16x32_bf16 v[38:41], v[154:157], v[202:205], v[38:41]
	v_mfma_f32_16x16x32_bf16 v[30:33], v[162:165], v[202:205], v[30:33]
	v_mfma_f32_16x16x32_bf16 v[22:25], v[154:157], v[210:213], v[22:25]
	v_mfma_f32_16x16x32_bf16 v[14:17], v[162:165], v[210:213], v[14:17]
	v_mfma_f32_16x16x32_bf16 v[62:65], v[158:161], v[190:193], v[62:65]
	v_mfma_f32_16x16x32_bf16 v[58:61], v[166:169], v[190:193], v[58:61]
	v_mfma_f32_16x16x32_bf16 v[54:57], v[158:161], v[198:201], v[54:57]
	v_mfma_f32_16x16x32_bf16 v[46:49], v[166:169], v[198:201], v[46:49]
	v_mfma_f32_16x16x32_bf16 v[38:41], v[158:161], v[206:209], v[38:41]
	v_mfma_f32_16x16x32_bf16 v[30:33], v[166:169], v[206:209], v[30:33]
	v_mfma_f32_16x16x32_bf16 v[22:25], v[158:161], v[214:217], v[22:25]
	v_mfma_f32_16x16x32_bf16 v[14:17], v[166:169], v[214:217], v[14:17]
	s_setprio 0
	s_setprio 1
	v_mfma_f32_16x16x32_bf16 v[50:53], v[170:173], v[186:189], v[50:53]
	v_mfma_f32_16x16x32_bf16 v[42:45], v[178:181], v[186:189], v[42:45]
	v_mfma_f32_16x16x32_bf16 v[34:37], v[170:173], v[194:197], v[34:37]
	v_mfma_f32_16x16x32_bf16 v[26:29], v[178:181], v[194:197], v[26:29]
	v_mfma_f32_16x16x32_bf16 v[18:21], v[170:173], v[202:205], v[18:21]
	v_mfma_f32_16x16x32_bf16 v[10:13], v[178:181], v[202:205], v[10:13]
	v_mfma_f32_16x16x32_bf16 v[6:9], v[170:173], v[210:213], v[6:9]
	v_mfma_f32_16x16x32_bf16 v[2:5], v[178:181], v[210:213], v[2:5]
	v_mfma_f32_16x16x32_bf16 v[50:53], v[174:177], v[190:193], v[50:53]
	v_mfma_f32_16x16x32_bf16 v[42:45], v[182:185], v[190:193], v[42:45]
	v_mfma_f32_16x16x32_bf16 v[34:37], v[174:177], v[198:201], v[34:37]
	v_mfma_f32_16x16x32_bf16 v[26:29], v[182:185], v[198:201], v[26:29]
	v_mfma_f32_16x16x32_bf16 v[18:21], v[174:177], v[206:209], v[18:21]
	v_mfma_f32_16x16x32_bf16 v[10:13], v[182:185], v[206:209], v[10:13]
	v_mfma_f32_16x16x32_bf16 v[6:9], v[174:177], v[214:217], v[6:9]
	v_mfma_f32_16x16x32_bf16 v[2:5], v[182:185], v[214:217], v[2:5]
	s_setprio 0
	s_barrier
	s_cbranch_scc0 .LBB0_1241
	s_and_b64 vcc, exec, s[10:11]
	s_cbranch_vccz .LBB0_1244
	s_barrier
